# GEMM loops: address add placed between the m0 write and the LDS-DMA load instead of a pad s_nop
# baseline (speedup 1.0000x reference)
; #define PG8_STAGE(bufoff, gbase, voff) do { _Pragma("unroll") for (int _i = 0; _i < 2; ++_i) \
;         __builtin_amdgcn_global_load_lds((const unsigned*)((const char*)(gbase) + (voff)[_i]), (LAS unsigned*)(lds + (bufoff) + ldsw + _i * 8192), 16, 0, 0); } while (0)
; #define PG8_LDA(dst, b, h) do { _Pragma("unroll") for (int m = 0; m < 4; ++m) _Pragma("unroll") for (int k = 0; k < 2; ++k) dst[m][k] = *(const LAS bf16x8*)(lds + PG8_SA(b, h) + aoff + m * 2048 + k * 1024); } while (0)
; #define PG8_LDB(dst, b, h) do { _Pragma("unroll") for (int n = 0; n < 2; ++n) _Pragma("unroll") for (int k = 0; k < 2; ++k) dst[n][k] = *(const LAS bf16x8*)(lds + PG8_SB(b, h) + boff + n * 2048 + k * 1024); } while (0)
; #define PG8_MMA(ai, bj, At, Bt) do { __builtin_amdgcn_s_setprio(1); _Pragma("unroll") for (int m = 0; m < 4; ++m) _Pragma("unroll") for (int n = 0; n < 2; ++n) _Pragma("unroll") for (int k = 0; k < 2; ++k) \
;         acc[ai][bj][m][n] = __builtin_amdgcn_mfma_f32_16x16x32_bf16(Bt[n][k], At[m][k], acc[ai][bj][m][n], 0, 0, 0); __builtin_amdgcn_s_setprio(0); } while (0)
; #define PG8_WAIT_V(n) asm volatile("s_waitcnt vmcnt(" #n ")" ::: "memory")
; #define PG8_WAIT_L(n) asm volatile("s_waitcnt lgkmcnt(" #n ")" ::: "memory")
; #define PG8_BAR __builtin_amdgcn_s_barrier()
; #define PG8_SCHED __builtin_amdgcn_sched_barrier(0)
; template <class Epi, class Sched>
; __device__ __forceinline__ void gemm_phase(LAS unsigned char* lds, const Gemm g, const Sched& S, const Epi& E, const int wave_s) {
;     ...
;             PG8_LDB(B0, 0, 0); PG8_LDB(B1, 0, 1); PG8_SCHED; PG8_LDA(At, 0, 0); PG8_STAGE(PG8_SA(1, 1), a1 + hstepA, voffA);
;             PG8_WAIT_V(8); PG8_WAIT_L(0); PG8_BAR; PG8_MMA(0, 0, At, B0); PG8_MMA(0, 1, At, B1); PG8_BAR; PG8_SCHED;
;             PG8_LDA(At, 0, 1); PG8_STAGE(PG8_SB(0, 0), b2, voffB); PG8_STAGE(PG8_SB(0, 1), b2 + hstepB, voffB); PG8_STAGE(PG8_SA(0, 0), a2, voffA);
;             PG8_WAIT_V(8); PG8_WAIT_L(0); PG8_BAR; PG8_MMA(1, 0, At, B0); PG8_MMA(1, 1, At, B1); PG8_BAR; PG8_SCHED;
.LBB0_125:
	ds_read_b128 v[152:155], v149
	ds_read_b128 v[156:159], v149 offset:1024
	ds_read_b128 v[160:163], v149 offset:2048
	ds_read_b128 v[164:167], v149 offset:3072
	ds_read_b128 v[168:171], v150
	ds_read_b128 v[172:175], v150 offset:1024
	ds_read_b128 v[176:179], v150 offset:2048
	ds_read_b128 v[180:183], v150 offset:3072
	s_add_u32 s4, s44, 0xfffc0080
	s_addc_u32 s5, s45, -1
	s_cmp_eq_u32 s65, 12
	s_cselect_b32 s47, s29, s5
	s_cselect_b32 s46, s61, s4
	s_cselect_b32 s5, s27, s64
	s_cselect_b32 s4, s62, s63
	v_lshl_add_u64 v[144:145], s[44:45], 0, v[136:137]
	s_add_i32 m0, s33, 0xc000
	ds_read_b128 v[184:187], v151
	ds_read_b128 v[188:191], v151 offset:1024
	ds_read_b128 v[192:195], v151 offset:2048
	ds_read_b128 v[196:199], v151 offset:3072
	ds_read_b128 v[200:203], v151 offset:4096
	ds_read_b128 v[204:207], v151 offset:5120
	ds_read_b128 v[210:213], v151 offset:6144
	ds_read_b128 v[214:217], v151 offset:7168
	global_load_lds_dwordx4 v[144:145], off
	s_add_i32 m0, s33, 0xe000
	v_lshl_add_u64 v[144:145], s[44:45], 0, v[138:139]
	global_load_lds_dwordx4 v[144:145], off
	s_waitcnt vmcnt(8) lgkmcnt(0)
	s_barrier
	s_setprio 1
	v_mfma_f32_16x16x32_bf16 v[124:127], v[152:155], v[184:187], v[124:127]
	v_mfma_f32_16x16x32_bf16 v[120:123], v[160:163], v[184:187], v[120:123]
	v_mfma_f32_16x16x32_bf16 v[116:119], v[152:155], v[192:195], v[116:119]
	v_mfma_f32_16x16x32_bf16 v[108:111], v[160:163], v[192:195], v[108:111]
	v_mfma_f32_16x16x32_bf16 v[100:103], v[152:155], v[200:203], v[100:103]
	v_mfma_f32_16x16x32_bf16 v[92:95], v[160:163], v[200:203], v[92:95]
	v_mfma_f32_16x16x32_bf16 v[84:87], v[152:155], v[210:213], v[84:87]
	v_mfma_f32_16x16x32_bf16 v[76:79], v[160:163], v[210:213], v[76:79]
	v_mfma_f32_16x16x32_bf16 v[124:127], v[156:159], v[188:191], v[124:127]
	v_mfma_f32_16x16x32_bf16 v[120:123], v[164:167], v[188:191], v[120:123]
	v_mfma_f32_16x16x32_bf16 v[116:119], v[156:159], v[196:199], v[116:119]
	v_mfma_f32_16x16x32_bf16 v[108:111], v[164:167], v[196:199], v[108:111]
	v_mfma_f32_16x16x32_bf16 v[100:103], v[156:159], v[204:207], v[100:103]
	v_mfma_f32_16x16x32_bf16 v[92:95], v[164:167], v[204:207], v[92:95]
	v_mfma_f32_16x16x32_bf16 v[84:87], v[156:159], v[214:217], v[84:87]
	v_mfma_f32_16x16x32_bf16 v[76:79], v[164:167], v[214:217], v[76:79]
	s_setprio 0
	s_setprio 1
	v_mfma_f32_16x16x32_bf16 v[112:115], v[168:171], v[184:187], v[112:115]
	v_mfma_f32_16x16x32_bf16 v[104:107], v[176:179], v[184:187], v[104:107]
	v_mfma_f32_16x16x32_bf16 v[96:99], v[168:171], v[192:195], v[96:99]
	v_mfma_f32_16x16x32_bf16 v[88:91], v[176:179], v[192:195], v[88:91]
	v_mfma_f32_16x16x32_bf16 v[80:83], v[168:171], v[200:203], v[80:83]
	v_mfma_f32_16x16x32_bf16 v[72:75], v[176:179], v[200:203], v[72:75]
	v_mfma_f32_16x16x32_bf16 v[68:71], v[168:171], v[210:213], v[68:71]
	v_mfma_f32_16x16x32_bf16 v[64:67], v[176:179], v[210:213], v[64:67]
	v_mfma_f32_16x16x32_bf16 v[112:115], v[172:175], v[188:191], v[112:115]
	v_mfma_f32_16x16x32_bf16 v[104:107], v[180:183], v[188:191], v[104:107]
	v_mfma_f32_16x16x32_bf16 v[96:99], v[172:175], v[196:199], v[96:99]
	v_mfma_f32_16x16x32_bf16 v[88:91], v[180:183], v[196:199], v[88:91]
	v_mfma_f32_16x16x32_bf16 v[80:83], v[172:175], v[204:207], v[80:83]
	v_mfma_f32_16x16x32_bf16 v[72:75], v[180:183], v[204:207], v[72:75]
	v_mfma_f32_16x16x32_bf16 v[68:71], v[172:175], v[214:217], v[68:71]
	v_mfma_f32_16x16x32_bf16 v[64:67], v[180:183], v[214:217], v[64:67]
	s_setprio 0
	s_barrier
	s_add_i32 s66, s53, s81
	v_lshl_add_u64 v[144:145], s[4:5], 0, v[130:131]
	s_mov_b32 m0, s66
	ds_read_b128 v[184:187], v151 offset:16384
	ds_read_b128 v[188:191], v151 offset:17408
	ds_read_b128 v[192:195], v151 offset:18432
	ds_read_b128 v[196:199], v151 offset:19456
	ds_read_b128 v[200:203], v151 offset:20480
	ds_read_b128 v[204:207], v151 offset:21504
	ds_read_b128 v[210:213], v151 offset:22528
	ds_read_b128 v[214:217], v151 offset:23552
	global_load_lds_dwordx4 v[144:145], off
	s_add_i32 m0, s66, 0x2000
	s_add_u32 s66, s4, 0x40000
	v_lshl_add_u64 v[218:219], s[4:5], 0, v[134:135]
	s_addc_u32 s67, s5, 0
	s_add_i32 s68, s54, s81
	global_load_lds_dwordx4 v[218:219], off
	v_lshl_add_u64 v[220:221], s[66:67], 0, v[130:131]
	s_mov_b32 m0, s68
	v_lshl_add_u64 v[222:223], s[46:47], 0, v[132:133]
	global_load_lds_dwordx4 v[220:221], off
	s_add_i32 m0, s68, 0x2000
	v_lshl_add_u64 v[220:221], s[66:67], 0, v[134:135]
	global_load_lds_dwordx4 v[220:221], off
	s_mov_b32 m0, s33
	v_lshl_add_u64 v[220:221], s[46:47], 0, v[128:129]
	global_load_lds_dwordx4 v[220:221], off
	s_mov_b32 m0, s35
	s_nop 0
	global_load_lds_dwordx4 v[222:223], off
	s_waitcnt vmcnt(8) lgkmcnt(0)
	s_barrier
; #define PG8_STAGE(bufoff, gbase, voff) do { _Pragma("unroll") for (int _i = 0; _i < 2; ++_i) \
;         __builtin_amdgcn_global_load_lds((const unsigned*)((const char*)(gbase) + (voff)[_i]), (LAS unsigned*)(lds + (bufoff) + ldsw + _i * 8192), 16, 0, 0); } while (0)
; #define PG8_LDA(dst, b, h) do { _Pragma("unroll") for (int m = 0; m < 4; ++m) _Pragma("unroll") for (int k = 0; k < 2; ++k) dst[m][k] = *(const LAS bf16x8*)(lds + PG8_SA(b, h) + aoff + m * 2048 + k * 1024); } while (0)
; #define PG8_LDB(dst, b, h) do { _Pragma("unroll") for (int n = 0; n < 2; ++n) _Pragma("unroll") for (int k = 0; k < 2; ++k) dst[n][k] = *(const LAS bf16x8*)(lds + PG8_SB(b, h) + boff + n * 2048 + k * 1024); } while (0)
; #define PG8_MMA(ai, bj, At, Bt) do { __builtin_amdgcn_s_setprio(1); _Pragma("unroll") for (int m = 0; m < 4; ++m) _Pragma("unroll") for (int n = 0; n < 2; ++n) _Pragma("unroll") for (int k = 0; k < 2; ++k) \
;         acc[ai][bj][m][n] = __builtin_amdgcn_mfma_f32_16x16x32_bf16(Bt[n][k], At[m][k], acc[ai][bj][m][n], 0, 0, 0); __builtin_amdgcn_s_setprio(0); } while (0)
; #define PG8_WAIT_V(n) asm volatile("s_waitcnt vmcnt(" #n ")" ::: "memory")
; #define PG8_WAIT_L(n) asm volatile("s_waitcnt lgkmcnt(" #n ")" ::: "memory")
; #define PG8_BAR __builtin_amdgcn_s_barrier()
; #define PG8_SCHED __builtin_amdgcn_sched_barrier(0)
; template <class Epi, class Sched>
; __device__ __forceinline__ void gemm_phase(LAS unsigned char* lds, const Gemm g, const Sched& S, const Epi& E, const int wave_s) {
;     ...
;             PG8_WAIT_V(8); PG8_WAIT_L(0); PG8_BAR; PG8_MMA(1, 0, At, B0); PG8_MMA(1, 1, At, B1); PG8_BAR; PG8_SCHED;
;             PG8_LDB(B0, 1, 0); PG8_LDB(B1, 1, 1); PG8_SCHED; PG8_LDA(At, 1, 0); PG8_STAGE(PG8_SA(0, 1), a2 + hstepA, voffA);
;             PG8_WAIT_V(8); PG8_WAIT_L(0); PG8_BAR; PG8_MMA(0, 0, At, B0); PG8_MMA(0, 1, At, B1); PG8_BAR; PG8_SCHED;
	s_setprio 1
	v_mfma_f32_16x16x32_bf16 v[60:63], v[152:155], v[184:187], v[60:63]
	v_mfma_f32_16x16x32_bf16 v[56:59], v[160:163], v[184:187], v[56:59]
	v_mfma_f32_16x16x32_bf16 v[52:55], v[152:155], v[192:195], v[52:55]
	v_mfma_f32_16x16x32_bf16 v[44:47], v[160:163], v[192:195], v[44:47]
	v_mfma_f32_16x16x32_bf16 v[36:39], v[152:155], v[200:203], v[36:39]
	v_mfma_f32_16x16x32_bf16 v[28:31], v[160:163], v[200:203], v[28:31]
	v_mfma_f32_16x16x32_bf16 v[20:23], v[152:155], v[210:213], v[20:23]
	v_mfma_f32_16x16x32_bf16 v[12:15], v[160:163], v[210:213], v[12:15]
	v_mfma_f32_16x16x32_bf16 v[60:63], v[156:159], v[188:191], v[60:63]
	v_mfma_f32_16x16x32_bf16 v[56:59], v[164:167], v[188:191], v[56:59]
	v_mfma_f32_16x16x32_bf16 v[52:55], v[156:159], v[196:199], v[52:55]
	v_mfma_f32_16x16x32_bf16 v[44:47], v[164:167], v[196:199], v[44:47]
	v_mfma_f32_16x16x32_bf16 v[36:39], v[156:159], v[204:207], v[36:39]
	v_mfma_f32_16x16x32_bf16 v[28:31], v[164:167], v[204:207], v[28:31]
	v_mfma_f32_16x16x32_bf16 v[20:23], v[156:159], v[214:217], v[20:23]
	v_mfma_f32_16x16x32_bf16 v[12:15], v[164:167], v[214:217], v[12:15]
	s_setprio 0
	s_setprio 1
	v_mfma_f32_16x16x32_bf16 v[48:51], v[168:171], v[184:187], v[48:51]
	v_mfma_f32_16x16x32_bf16 v[40:43], v[176:179], v[184:187], v[40:43]
	v_mfma_f32_16x16x32_bf16 v[32:35], v[168:171], v[192:195], v[32:35]
	v_mfma_f32_16x16x32_bf16 v[24:27], v[176:179], v[192:195], v[24:27]
	v_mfma_f32_16x16x32_bf16 v[16:19], v[168:171], v[200:203], v[16:19]
	v_mfma_f32_16x16x32_bf16 v[8:11], v[176:179], v[200:203], v[8:11]
	v_mfma_f32_16x16x32_bf16 v[4:7], v[168:171], v[210:213], v[4:7]
	v_mfma_f32_16x16x32_bf16 v[0:3], v[176:179], v[210:213], v[0:3]
	v_mfma_f32_16x16x32_bf16 v[48:51], v[172:175], v[188:191], v[48:51]
	v_mfma_f32_16x16x32_bf16 v[40:43], v[180:183], v[188:191], v[40:43]
	v_mfma_f32_16x16x32_bf16 v[32:35], v[172:175], v[196:199], v[32:35]
	v_mfma_f32_16x16x32_bf16 v[24:27], v[180:183], v[196:199], v[24:27]
	v_mfma_f32_16x16x32_bf16 v[16:19], v[172:175], v[204:207], v[16:19]
	v_mfma_f32_16x16x32_bf16 v[8:11], v[180:183], v[204:207], v[8:11]
	v_mfma_f32_16x16x32_bf16 v[4:7], v[172:175], v[214:217], v[4:7]
	v_mfma_f32_16x16x32_bf16 v[0:3], v[180:183], v[214:217], v[0:3]
	s_setprio 0
	s_barrier
	s_add_i32 s66, 0, 0x18000
	s_add_i32 s67, 0, 0x1c000
	v_add_u32_e32 v164, s66, v147
	v_add_u32_e32 v180, s67, v147
	ds_read_b128 v[152:155], v164
	ds_read_b128 v[156:159], v164 offset:1024
	ds_read_b128 v[160:163], v164 offset:2048
	ds_read_b128 v[164:167], v164 offset:3072
	ds_read_b128 v[168:171], v180
	ds_read_b128 v[172:175], v180 offset:1024
	ds_read_b128 v[176:179], v180 offset:2048
	ds_read_b128 v[180:183], v180 offset:3072
	s_add_u32 s46, s46, 0x40000
	s_addc_u32 s47, s47, 0
	s_mov_b32 m0, s37
	v_lshl_add_u64 v[224:225], s[46:47], 0, v[128:129]
	ds_read_b128 v[184:187], v151 offset:32768
	ds_read_b128 v[188:191], v151 offset:33792
	ds_read_b128 v[192:195], v151 offset:34816
	ds_read_b128 v[196:199], v151 offset:35840
	ds_read_b128 v[200:203], v151 offset:36864
	ds_read_b128 v[204:207], v151 offset:37888
	ds_read_b128 v[210:213], v151 offset:38912
	ds_read_b128 v[214:217], v151 offset:39936
	global_load_lds_dwordx4 v[224:225], off
	s_mov_b32 m0, s43
	v_lshl_add_u64 v[224:225], s[46:47], 0, v[132:133]
	global_load_lds_dwordx4 v[224:225], off
	s_waitcnt vmcnt(8) lgkmcnt(0)
	s_barrier
	s_setprio 1
	v_mfma_f32_16x16x32_bf16 v[124:127], v[152:155], v[184:187], v[124:127]
	v_mfma_f32_16x16x32_bf16 v[120:123], v[160:163], v[184:187], v[120:123]
	v_mfma_f32_16x16x32_bf16 v[116:119], v[152:155], v[192:195], v[116:119]
	v_mfma_f32_16x16x32_bf16 v[108:111], v[160:163], v[192:195], v[108:111]
	v_mfma_f32_16x16x32_bf16 v[100:103], v[152:155], v[200:203], v[100:103]
	v_mfma_f32_16x16x32_bf16 v[92:95], v[160:163], v[200:203], v[92:95]
	v_mfma_f32_16x16x32_bf16 v[84:87], v[152:155], v[210:213], v[84:87]
	v_mfma_f32_16x16x32_bf16 v[76:79], v[160:163], v[210:213], v[76:79]
	v_mfma_f32_16x16x32_bf16 v[124:127], v[156:159], v[188:191], v[124:127]
	v_mfma_f32_16x16x32_bf16 v[120:123], v[164:167], v[188:191], v[120:123]
	v_mfma_f32_16x16x32_bf16 v[116:119], v[156:159], v[196:199], v[116:119]
	v_mfma_f32_16x16x32_bf16 v[108:111], v[164:167], v[196:199], v[108:111]
	v_mfma_f32_16x16x32_bf16 v[100:103], v[156:159], v[204:207], v[100:103]
	v_mfma_f32_16x16x32_bf16 v[92:95], v[164:167], v[204:207], v[92:95]
	v_mfma_f32_16x16x32_bf16 v[84:87], v[156:159], v[214:217], v[84:87]
	v_mfma_f32_16x16x32_bf16 v[76:79], v[164:167], v[214:217], v[76:79]
	s_setprio 0
	s_setprio 1
	v_mfma_f32_16x16x32_bf16 v[112:115], v[168:171], v[184:187], v[112:115]
	v_mfma_f32_16x16x32_bf16 v[104:107], v[176:179], v[184:187], v[104:107]
	v_mfma_f32_16x16x32_bf16 v[96:99], v[168:171], v[192:195], v[96:99]
	v_mfma_f32_16x16x32_bf16 v[88:91], v[176:179], v[192:195], v[88:91]
	v_mfma_f32_16x16x32_bf16 v[80:83], v[168:171], v[200:203], v[80:83]
	v_mfma_f32_16x16x32_bf16 v[72:75], v[176:179], v[200:203], v[72:75]
	v_mfma_f32_16x16x32_bf16 v[68:71], v[168:171], v[210:213], v[68:71]
	v_mfma_f32_16x16x32_bf16 v[64:67], v[176:179], v[210:213], v[64:67]
	v_mfma_f32_16x16x32_bf16 v[112:115], v[172:175], v[188:191], v[112:115]
	v_mfma_f32_16x16x32_bf16 v[104:107], v[180:183], v[188:191], v[104:107]
	v_mfma_f32_16x16x32_bf16 v[96:99], v[172:175], v[196:199], v[96:99]
	v_mfma_f32_16x16x32_bf16 v[88:91], v[180:183], v[196:199], v[88:91]
	v_mfma_f32_16x16x32_bf16 v[80:83], v[172:175], v[204:207], v[80:83]
	v_mfma_f32_16x16x32_bf16 v[72:75], v[180:183], v[204:207], v[72:75]
	v_mfma_f32_16x16x32_bf16 v[68:71], v[172:175], v[214:217], v[68:71]
	v_mfma_f32_16x16x32_bf16 v[64:67], v[180:183], v[214:217], v[64:67]
	s_setprio 0
	s_barrier
; #define PG8_STAGE(bufoff, gbase, voff) do { _Pragma("unroll") for (int _i = 0; _i < 2; ++_i) \
;         __builtin_amdgcn_global_load_lds((const unsigned*)((const char*)(gbase) + (voff)[_i]), (LAS unsigned*)(lds + (bufoff) + ldsw + _i * 8192), 16, 0, 0); } while (0)
; #define PG8_LDA(dst, b, h) do { _Pragma("unroll") for (int m = 0; m < 4; ++m) _Pragma("unroll") for (int k = 0; k < 2; ++k) dst[m][k] = *(const LAS bf16x8*)(lds + PG8_SA(b, h) + aoff + m * 2048 + k * 1024); } while (0)
; #define PG8_MMA(ai, bj, At, Bt) do { __builtin_amdgcn_s_setprio(1); _Pragma("unroll") for (int m = 0; m < 4; ++m) _Pragma("unroll") for (int n = 0; n < 2; ++n) _Pragma("unroll") for (int k = 0; k < 2; ++k) \
;         acc[ai][bj][m][n] = __builtin_amdgcn_mfma_f32_16x16x32_bf16(Bt[n][k], At[m][k], acc[ai][bj][m][n], 0, 0, 0); __builtin_amdgcn_s_setprio(0); } while (0)
; #define PG8_WAIT_V(n) asm volatile("s_waitcnt vmcnt(" #n ")" ::: "memory")
; #define PG8_WAIT_L(n) asm volatile("s_waitcnt lgkmcnt(" #n ")" ::: "memory")
; #define PG8_BAR __builtin_amdgcn_s_barrier()
; #define PG8_SCHED __builtin_amdgcn_sched_barrier(0)
; template <class Epi, class Sched>
; __device__ __forceinline__ void gemm_phase(LAS unsigned char* lds, const Gemm g, const Sched& S, const Epi& E, const int wave_s) {
;     ...
;             PG8_LDA(At, 1, 1); PG8_STAGE(PG8_SB(1, 0), b3, voffB); PG8_STAGE(PG8_SB(1, 1), b3 + hstepB, voffB); PG8_STAGE(PG8_SA(1, 0), a3, voffA);
;             PG8_WAIT_V(8); PG8_WAIT_L(0); PG8_BAR; PG8_MMA(1, 0, At, B0); PG8_MMA(1, 1, At, B1); PG8_BAR; PG8_SCHED;
;         }
;         if (wr == 0) PG8_BAR;
	s_add_i32 s46, s66, s81
	v_lshl_add_u64 v[144:145], v[144:145], 0, s[14:15]
	s_mov_b32 m0, s46
	ds_read_b128 v[184:187], v151 offset:49152
	ds_read_b128 v[188:191], v151 offset:50176
	ds_read_b128 v[192:195], v151 offset:51200
	ds_read_b128 v[196:199], v151 offset:52224
	ds_read_b128 v[200:203], v151 offset:53248
	ds_read_b128 v[204:207], v151 offset:54272
	ds_read_b128 v[210:213], v151 offset:55296
	ds_read_b128 v[214:217], v151 offset:56320
	global_load_lds_dwordx4 v[144:145], off
	s_add_i32 m0, s46, 0x2000
	s_add_u32 s4, s4, 0x40080
	v_lshl_add_u64 v[144:145], v[218:219], 0, s[14:15]
	s_addc_u32 s5, s5, 0
	s_add_i32 s46, s67, s81
	global_load_lds_dwordx4 v[144:145], off
	s_mov_b32 m0, s46
	v_lshl_add_u64 v[144:145], s[4:5], 0, v[130:131]
	global_load_lds_dwordx4 v[144:145], off
	s_add_i32 m0, s46, 0x2000
	v_lshl_add_u64 v[144:145], s[4:5], 0, v[134:135]
	global_load_lds_dwordx4 v[144:145], off
	s_mov_b32 m0, s49
	v_lshl_add_u64 v[144:145], v[220:221], 0, s[14:15]
	global_load_lds_dwordx4 v[144:145], off
	s_mov_b32 m0, s50
	v_lshl_add_u64 v[144:145], v[222:223], 0, s[14:15]
	global_load_lds_dwordx4 v[144:145], off
	s_waitcnt vmcnt(8) lgkmcnt(0)
	s_barrier
	s_setprio 1
	v_mfma_f32_16x16x32_bf16 v[60:63], v[152:155], v[184:187], v[60:63]
	v_mfma_f32_16x16x32_bf16 v[56:59], v[160:163], v[184:187], v[56:59]
	v_mfma_f32_16x16x32_bf16 v[52:55], v[152:155], v[192:195], v[52:55]
	v_mfma_f32_16x16x32_bf16 v[44:47], v[160:163], v[192:195], v[44:47]
	v_mfma_f32_16x16x32_bf16 v[36:39], v[152:155], v[200:203], v[36:39]
	v_mfma_f32_16x16x32_bf16 v[28:31], v[160:163], v[200:203], v[28:31]
	v_mfma_f32_16x16x32_bf16 v[20:23], v[152:155], v[210:213], v[20:23]
	v_mfma_f32_16x16x32_bf16 v[12:15], v[160:163], v[210:213], v[12:15]
	v_mfma_f32_16x16x32_bf16 v[60:63], v[156:159], v[188:191], v[60:63]
	v_mfma_f32_16x16x32_bf16 v[56:59], v[164:167], v[188:191], v[56:59]
	v_mfma_f32_16x16x32_bf16 v[52:55], v[156:159], v[196:199], v[52:55]
	v_mfma_f32_16x16x32_bf16 v[44:47], v[164:167], v[196:199], v[44:47]
	v_mfma_f32_16x16x32_bf16 v[36:39], v[156:159], v[204:207], v[36:39]
	v_mfma_f32_16x16x32_bf16 v[28:31], v[164:167], v[204:207], v[28:31]
	v_mfma_f32_16x16x32_bf16 v[20:23], v[156:159], v[214:217], v[20:23]
	v_mfma_f32_16x16x32_bf16 v[12:15], v[164:167], v[214:217], v[12:15]
	s_setprio 0
	s_setprio 1
	v_mfma_f32_16x16x32_bf16 v[48:51], v[168:171], v[184:187], v[48:51]
	v_mfma_f32_16x16x32_bf16 v[40:43], v[176:179], v[184:187], v[40:43]
	v_mfma_f32_16x16x32_bf16 v[32:35], v[168:171], v[192:195], v[32:35]
	v_mfma_f32_16x16x32_bf16 v[24:27], v[176:179], v[192:195], v[24:27]
	v_mfma_f32_16x16x32_bf16 v[16:19], v[168:171], v[200:203], v[16:19]
	v_mfma_f32_16x16x32_bf16 v[8:11], v[176:179], v[200:203], v[8:11]
	v_mfma_f32_16x16x32_bf16 v[4:7], v[168:171], v[210:213], v[4:7]
	v_mfma_f32_16x16x32_bf16 v[0:3], v[176:179], v[210:213], v[0:3]
	v_mfma_f32_16x16x32_bf16 v[48:51], v[172:175], v[188:191], v[48:51]
	v_mfma_f32_16x16x32_bf16 v[40:43], v[180:183], v[188:191], v[40:43]
	v_mfma_f32_16x16x32_bf16 v[32:35], v[172:175], v[196:199], v[32:35]
	v_mfma_f32_16x16x32_bf16 v[24:27], v[180:183], v[196:199], v[24:27]
	v_mfma_f32_16x16x32_bf16 v[16:19], v[172:175], v[204:207], v[16:19]
	v_mfma_f32_16x16x32_bf16 v[8:11], v[180:183], v[204:207], v[8:11]
	v_mfma_f32_16x16x32_bf16 v[4:7], v[172:175], v[214:217], v[4:7]
	v_mfma_f32_16x16x32_bf16 v[0:3], v[180:183], v[214:217], v[0:3]
	s_setprio 0
	s_barrier
	s_add_i32 s65, s65, 2
	s_add_u32 s44, s44, 0x100
	s_addc_u32 s45, s45, 0
	s_add_u32 s63, s63, 0x100
	s_addc_u32 s64, s64, 0
	s_cmp_gt_u32 s65, 13
	s_cbranch_scc0 .LBB0_125
	s_and_b64 vcc, exec, s[16:17]
	s_cbranch_vccz .LBB0_128
	s_barrier

; #define PG8_STAGE(bufoff, gbase, voff) do { _Pragma("unroll") for (int _i = 0; _i < 2; ++_i) \
;         __builtin_amdgcn_global_load_lds((const unsigned*)((const char*)(gbase) + (voff)[_i]), (LAS unsigned*)(lds + (bufoff) + ldsw + _i * 8192), 16, 0, 0); } while (0)
; #define PG8_LDA(dst, b, h) do { _Pragma("unroll") for (int m = 0; m < 4; ++m) _Pragma("unroll") for (int k = 0; k < 2; ++k) dst[m][k] = *(const LAS bf16x8*)(lds + PG8_SA(b, h) + aoff + m * 2048 + k * 1024); } while (0)
; #define PG8_LDB(dst, b, h) do { _Pragma("unroll") for (int n = 0; n < 2; ++n) _Pragma("unroll") for (int k = 0; k < 2; ++k) dst[n][k] = *(const LAS bf16x8*)(lds + PG8_SB(b, h) + boff + n * 2048 + k * 1024); } while (0)
; #define PG8_MMA(ai, bj, At, Bt) do { __builtin_amdgcn_s_setprio(1); _Pragma("unroll") for (int m = 0; m < 4; ++m) _Pragma("unroll") for (int n = 0; n < 2; ++n) _Pragma("unroll") for (int k = 0; k < 2; ++k) \
;         acc[ai][bj][m][n] = __builtin_amdgcn_mfma_f32_16x16x32_bf16(Bt[n][k], At[m][k], acc[ai][bj][m][n], 0, 0, 0); __builtin_amdgcn_s_setprio(0); } while (0)
; #define PG8_WAIT_V(n) asm volatile("s_waitcnt vmcnt(" #n ")" ::: "memory")
; #define PG8_WAIT_L(n) asm volatile("s_waitcnt lgkmcnt(" #n ")" ::: "memory")
; #define PG8_BAR __builtin_amdgcn_s_barrier()
; #define PG8_SCHED __builtin_amdgcn_sched_barrier(0)
; template <class Epi, class Sched>
; __device__ __forceinline__ void gemm_phase(LAS unsigned char* lds, const Gemm g, const Sched& S, const Epi& E, const int wave_s) {
;     ...
;             PG8_LDB(B0, 0, 0); PG8_LDB(B1, 0, 1); PG8_SCHED; PG8_LDA(At, 0, 0); PG8_STAGE(PG8_SA(1, 1), a1 + hstepA, voffA);
;             PG8_WAIT_V(8); PG8_WAIT_L(0); PG8_BAR; PG8_MMA(0, 0, At, B0); PG8_MMA(0, 1, At, B1); PG8_BAR; PG8_SCHED;
;             PG8_LDA(At, 0, 1); PG8_STAGE(PG8_SB(0, 0), b2, voffB); PG8_STAGE(PG8_SB(0, 1), b2 + hstepB, voffB); PG8_STAGE(PG8_SA(0, 0), a2, voffA);
;             PG8_WAIT_V(8); PG8_WAIT_L(0); PG8_BAR; PG8_MMA(1, 0, At, B0); PG8_MMA(1, 1, At, B1); PG8_BAR; PG8_SCHED;
.LBB0_194:
	ds_read_b128 v[144:147], v151
	ds_read_b128 v[154:157], v151 offset:1024
	ds_read_b128 v[158:161], v151 offset:2048
	ds_read_b128 v[162:165], v151 offset:3072
	ds_read_b128 v[166:169], v152
	ds_read_b128 v[170:173], v152 offset:1024
	ds_read_b128 v[174:177], v152 offset:2048
	ds_read_b128 v[178:181], v152 offset:3072
	s_add_u32 s4, s24, 0xfffc0080
	s_addc_u32 s5, s25, -1
	s_cmp_eq_u32 s54, 12
	s_cselect_b32 s27, s19, s5
	s_cselect_b32 s26, s50, s4
	s_cselect_b32 s5, s17, s53
	s_cselect_b32 s4, s51, s52
	v_lshl_add_u64 v[206:207], s[24:25], 0, v[136:137]
	s_add_i32 m0, s30, 0xc000
	ds_read_b128 v[182:185], v153
	ds_read_b128 v[186:189], v153 offset:1024
	ds_read_b128 v[190:193], v153 offset:2048
	ds_read_b128 v[194:197], v153 offset:3072
	ds_read_b128 v[198:201], v153 offset:4096
	ds_read_b128 v[202:205], v153 offset:5120
	ds_read_b128 v[210:213], v153 offset:6144
	ds_read_b128 v[214:217], v153 offset:7168
	global_load_lds_dwordx4 v[206:207], off
	s_add_i32 m0, s30, 0xe000
	v_lshl_add_u64 v[206:207], s[24:25], 0, v[138:139]
	global_load_lds_dwordx4 v[206:207], off
	s_waitcnt vmcnt(8) lgkmcnt(0)
	s_barrier
	s_setprio 1
	v_mfma_f32_16x16x32_bf16 v[124:127], v[144:147], v[182:185], v[124:127]
	v_mfma_f32_16x16x32_bf16 v[120:123], v[158:161], v[182:185], v[120:123]
	v_mfma_f32_16x16x32_bf16 v[116:119], v[144:147], v[190:193], v[116:119]
	v_mfma_f32_16x16x32_bf16 v[108:111], v[158:161], v[190:193], v[108:111]
	v_mfma_f32_16x16x32_bf16 v[100:103], v[144:147], v[198:201], v[100:103]
	v_mfma_f32_16x16x32_bf16 v[92:95], v[158:161], v[198:201], v[92:95]
	v_mfma_f32_16x16x32_bf16 v[84:87], v[144:147], v[210:213], v[84:87]
	v_mfma_f32_16x16x32_bf16 v[76:79], v[158:161], v[210:213], v[76:79]
	v_mfma_f32_16x16x32_bf16 v[124:127], v[154:157], v[186:189], v[124:127]
	v_mfma_f32_16x16x32_bf16 v[120:123], v[162:165], v[186:189], v[120:123]
	v_mfma_f32_16x16x32_bf16 v[116:119], v[154:157], v[194:197], v[116:119]
	v_mfma_f32_16x16x32_bf16 v[108:111], v[162:165], v[194:197], v[108:111]
	v_mfma_f32_16x16x32_bf16 v[100:103], v[154:157], v[202:205], v[100:103]
	v_mfma_f32_16x16x32_bf16 v[92:95], v[162:165], v[202:205], v[92:95]
	v_mfma_f32_16x16x32_bf16 v[84:87], v[154:157], v[214:217], v[84:87]
	v_mfma_f32_16x16x32_bf16 v[76:79], v[162:165], v[214:217], v[76:79]
	s_setprio 0
	s_setprio 1
	v_mfma_f32_16x16x32_bf16 v[112:115], v[166:169], v[182:185], v[112:115]
	v_mfma_f32_16x16x32_bf16 v[104:107], v[174:177], v[182:185], v[104:107]
	v_mfma_f32_16x16x32_bf16 v[96:99], v[166:169], v[190:193], v[96:99]
	v_mfma_f32_16x16x32_bf16 v[88:91], v[174:177], v[190:193], v[88:91]
	v_mfma_f32_16x16x32_bf16 v[80:83], v[166:169], v[198:201], v[80:83]
	v_mfma_f32_16x16x32_bf16 v[72:75], v[174:177], v[198:201], v[72:75]
	v_mfma_f32_16x16x32_bf16 v[68:71], v[166:169], v[210:213], v[68:71]
	v_mfma_f32_16x16x32_bf16 v[64:67], v[174:177], v[210:213], v[64:67]
	v_mfma_f32_16x16x32_bf16 v[112:115], v[170:173], v[186:189], v[112:115]
	v_mfma_f32_16x16x32_bf16 v[104:107], v[178:181], v[186:189], v[104:107]
	v_mfma_f32_16x16x32_bf16 v[96:99], v[170:173], v[194:197], v[96:99]
	v_mfma_f32_16x16x32_bf16 v[88:91], v[178:181], v[194:197], v[88:91]
	v_mfma_f32_16x16x32_bf16 v[80:83], v[170:173], v[202:205], v[80:83]
	v_mfma_f32_16x16x32_bf16 v[72:75], v[178:181], v[202:205], v[72:75]
	v_mfma_f32_16x16x32_bf16 v[68:71], v[170:173], v[214:217], v[68:71]
	v_mfma_f32_16x16x32_bf16 v[64:67], v[178:181], v[214:217], v[64:67]
	s_setprio 0
	s_barrier
	s_add_i32 s55, s45, s81
	v_lshl_add_u64 v[206:207], s[4:5], 0, v[132:133]
	s_mov_b32 m0, s55
	ds_read_b128 v[182:185], v153 offset:16384
	ds_read_b128 v[186:189], v153 offset:17408
	ds_read_b128 v[190:193], v153 offset:18432
	ds_read_b128 v[194:197], v153 offset:19456
	ds_read_b128 v[198:201], v153 offset:20480
	ds_read_b128 v[202:205], v153 offset:21504
	ds_read_b128 v[210:213], v153 offset:22528
	ds_read_b128 v[214:217], v153 offset:23552
	global_load_lds_dwordx4 v[206:207], off
	s_add_i32 m0, s55, 0x2000
	s_add_u32 s58, s4, 0x40000
	v_lshl_add_u64 v[218:219], s[4:5], 0, v[128:129]
	s_addc_u32 s59, s5, 0
	s_add_i32 s55, s46, s81
	global_load_lds_dwordx4 v[218:219], off
	v_lshl_add_u64 v[220:221], s[58:59], 0, v[132:133]
	s_mov_b32 m0, s55
	v_lshl_add_u64 v[222:223], s[26:27], 0, v[130:131]
	global_load_lds_dwordx4 v[220:221], off
	s_add_i32 m0, s55, 0x2000
	v_lshl_add_u64 v[220:221], s[58:59], 0, v[128:129]
	global_load_lds_dwordx4 v[220:221], off
	s_mov_b32 m0, s30
	v_lshl_add_u64 v[220:221], s[26:27], 0, v[134:135]
	global_load_lds_dwordx4 v[220:221], off
	s_mov_b32 m0, s31
	s_nop 0
	global_load_lds_dwordx4 v[222:223], off
	s_waitcnt vmcnt(8) lgkmcnt(0)
	s_barrier
; #define PG8_STAGE(bufoff, gbase, voff) do { _Pragma("unroll") for (int _i = 0; _i < 2; ++_i) \
;         __builtin_amdgcn_global_load_lds((const unsigned*)((const char*)(gbase) + (voff)[_i]), (LAS unsigned*)(lds + (bufoff) + ldsw + _i * 8192), 16, 0, 0); } while (0)
; #define PG8_LDA(dst, b, h) do { _Pragma("unroll") for (int m = 0; m < 4; ++m) _Pragma("unroll") for (int k = 0; k < 2; ++k) dst[m][k] = *(const LAS bf16x8*)(lds + PG8_SA(b, h) + aoff + m * 2048 + k * 1024); } while (0)
; #define PG8_LDB(dst, b, h) do { _Pragma("unroll") for (int n = 0; n < 2; ++n) _Pragma("unroll") for (int k = 0; k < 2; ++k) dst[n][k] = *(const LAS bf16x8*)(lds + PG8_SB(b, h) + boff + n * 2048 + k * 1024); } while (0)
; #define PG8_MMA(ai, bj, At, Bt) do { __builtin_amdgcn_s_setprio(1); _Pragma("unroll") for (int m = 0; m < 4; ++m) _Pragma("unroll") for (int n = 0; n < 2; ++n) _Pragma("unroll") for (int k = 0; k < 2; ++k) \
;         acc[ai][bj][m][n] = __builtin_amdgcn_mfma_f32_16x16x32_bf16(Bt[n][k], At[m][k], acc[ai][bj][m][n], 0, 0, 0); __builtin_amdgcn_s_setprio(0); } while (0)
; #define PG8_WAIT_V(n) asm volatile("s_waitcnt vmcnt(" #n ")" ::: "memory")
; #define PG8_WAIT_L(n) asm volatile("s_waitcnt lgkmcnt(" #n ")" ::: "memory")
; #define PG8_BAR __builtin_amdgcn_s_barrier()
; #define PG8_SCHED __builtin_amdgcn_sched_barrier(0)
; template <class Epi, class Sched>
; __device__ __forceinline__ void gemm_phase(LAS unsigned char* lds, const Gemm g, const Sched& S, const Epi& E, const int wave_s) {
;     ...
;             PG8_WAIT_V(8); PG8_WAIT_L(0); PG8_BAR; PG8_MMA(1, 0, At, B0); PG8_MMA(1, 1, At, B1); PG8_BAR; PG8_SCHED;
;             PG8_LDB(B0, 1, 0); PG8_LDB(B1, 1, 1); PG8_SCHED; PG8_LDA(At, 1, 0); PG8_STAGE(PG8_SA(0, 1), a2 + hstepA, voffA);
;             PG8_WAIT_V(8); PG8_WAIT_L(0); PG8_BAR; PG8_MMA(0, 0, At, B0); PG8_MMA(0, 1, At, B1); PG8_BAR; PG8_SCHED;
	s_setprio 1
	v_mfma_f32_16x16x32_bf16 v[60:63], v[144:147], v[182:185], v[60:63]
	v_mfma_f32_16x16x32_bf16 v[56:59], v[158:161], v[182:185], v[56:59]
	v_mfma_f32_16x16x32_bf16 v[52:55], v[144:147], v[190:193], v[52:55]
	v_mfma_f32_16x16x32_bf16 v[44:47], v[158:161], v[190:193], v[44:47]
	v_mfma_f32_16x16x32_bf16 v[36:39], v[144:147], v[198:201], v[36:39]
	v_mfma_f32_16x16x32_bf16 v[28:31], v[158:161], v[198:201], v[28:31]
	v_mfma_f32_16x16x32_bf16 v[20:23], v[144:147], v[210:213], v[20:23]
	v_mfma_f32_16x16x32_bf16 v[12:15], v[158:161], v[210:213], v[12:15]
	v_mfma_f32_16x16x32_bf16 v[60:63], v[154:157], v[186:189], v[60:63]
	v_mfma_f32_16x16x32_bf16 v[56:59], v[162:165], v[186:189], v[56:59]
	v_mfma_f32_16x16x32_bf16 v[52:55], v[154:157], v[194:197], v[52:55]
	v_mfma_f32_16x16x32_bf16 v[44:47], v[162:165], v[194:197], v[44:47]
	v_mfma_f32_16x16x32_bf16 v[36:39], v[154:157], v[202:205], v[36:39]
	v_mfma_f32_16x16x32_bf16 v[28:31], v[162:165], v[202:205], v[28:31]
	v_mfma_f32_16x16x32_bf16 v[20:23], v[154:157], v[214:217], v[20:23]
	v_mfma_f32_16x16x32_bf16 v[12:15], v[162:165], v[214:217], v[12:15]
	s_setprio 0
	s_setprio 1
	v_mfma_f32_16x16x32_bf16 v[48:51], v[166:169], v[182:185], v[48:51]
	v_mfma_f32_16x16x32_bf16 v[40:43], v[174:177], v[182:185], v[40:43]
	v_mfma_f32_16x16x32_bf16 v[32:35], v[166:169], v[190:193], v[32:35]
	v_mfma_f32_16x16x32_bf16 v[24:27], v[174:177], v[190:193], v[24:27]
	v_mfma_f32_16x16x32_bf16 v[16:19], v[166:169], v[198:201], v[16:19]
	v_mfma_f32_16x16x32_bf16 v[8:11], v[174:177], v[198:201], v[8:11]
	v_mfma_f32_16x16x32_bf16 v[4:7], v[166:169], v[210:213], v[4:7]
	v_mfma_f32_16x16x32_bf16 v[0:3], v[174:177], v[210:213], v[0:3]
	v_mfma_f32_16x16x32_bf16 v[48:51], v[170:173], v[186:189], v[48:51]
	v_mfma_f32_16x16x32_bf16 v[40:43], v[178:181], v[186:189], v[40:43]
	v_mfma_f32_16x16x32_bf16 v[32:35], v[170:173], v[194:197], v[32:35]
	v_mfma_f32_16x16x32_bf16 v[24:27], v[178:181], v[194:197], v[24:27]
	v_mfma_f32_16x16x32_bf16 v[16:19], v[170:173], v[202:205], v[16:19]
	v_mfma_f32_16x16x32_bf16 v[8:11], v[178:181], v[202:205], v[8:11]
	v_mfma_f32_16x16x32_bf16 v[4:7], v[170:173], v[214:217], v[4:7]
	v_mfma_f32_16x16x32_bf16 v[0:3], v[178:181], v[214:217], v[0:3]
	s_setprio 0
	s_barrier
	s_add_i32 s55, 0, 0x18000
	s_add_i32 s57, 0, 0x1c000
	v_add_u32_e32 v162, s55, v149
	v_add_u32_e32 v178, s57, v149
	ds_read_b128 v[144:147], v162
	ds_read_b128 v[154:157], v162 offset:1024
	ds_read_b128 v[158:161], v162 offset:2048
	ds_read_b128 v[162:165], v162 offset:3072
	ds_read_b128 v[166:169], v178
	ds_read_b128 v[170:173], v178 offset:1024
	ds_read_b128 v[174:177], v178 offset:2048
	ds_read_b128 v[178:181], v178 offset:3072
	s_add_u32 s26, s26, 0x40000
	s_addc_u32 s27, s27, 0
	s_mov_b32 m0, s33
	v_lshl_add_u64 v[224:225], s[26:27], 0, v[134:135]
	ds_read_b128 v[182:185], v153 offset:32768
	ds_read_b128 v[186:189], v153 offset:33792
	ds_read_b128 v[190:193], v153 offset:34816
	ds_read_b128 v[194:197], v153 offset:35840
	ds_read_b128 v[198:201], v153 offset:36864
	ds_read_b128 v[202:205], v153 offset:37888
	ds_read_b128 v[210:213], v153 offset:38912
	ds_read_b128 v[214:217], v153 offset:39936
	global_load_lds_dwordx4 v[224:225], off
	s_mov_b32 m0, s35
	v_lshl_add_u64 v[224:225], s[26:27], 0, v[130:131]
	global_load_lds_dwordx4 v[224:225], off
	s_waitcnt vmcnt(8) lgkmcnt(0)
	s_barrier
	s_setprio 1
	v_mfma_f32_16x16x32_bf16 v[124:127], v[144:147], v[182:185], v[124:127]
	v_mfma_f32_16x16x32_bf16 v[120:123], v[158:161], v[182:185], v[120:123]
	v_mfma_f32_16x16x32_bf16 v[116:119], v[144:147], v[190:193], v[116:119]
	v_mfma_f32_16x16x32_bf16 v[108:111], v[158:161], v[190:193], v[108:111]
	v_mfma_f32_16x16x32_bf16 v[100:103], v[144:147], v[198:201], v[100:103]
	v_mfma_f32_16x16x32_bf16 v[92:95], v[158:161], v[198:201], v[92:95]
	v_mfma_f32_16x16x32_bf16 v[84:87], v[144:147], v[210:213], v[84:87]
	v_mfma_f32_16x16x32_bf16 v[76:79], v[158:161], v[210:213], v[76:79]
	v_mfma_f32_16x16x32_bf16 v[124:127], v[154:157], v[186:189], v[124:127]
	v_mfma_f32_16x16x32_bf16 v[120:123], v[162:165], v[186:189], v[120:123]
	v_mfma_f32_16x16x32_bf16 v[116:119], v[154:157], v[194:197], v[116:119]
	v_mfma_f32_16x16x32_bf16 v[108:111], v[162:165], v[194:197], v[108:111]
	v_mfma_f32_16x16x32_bf16 v[100:103], v[154:157], v[202:205], v[100:103]
	v_mfma_f32_16x16x32_bf16 v[92:95], v[162:165], v[202:205], v[92:95]
	v_mfma_f32_16x16x32_bf16 v[84:87], v[154:157], v[214:217], v[84:87]
	v_mfma_f32_16x16x32_bf16 v[76:79], v[162:165], v[214:217], v[76:79]
	s_setprio 0
	s_setprio 1
	v_mfma_f32_16x16x32_bf16 v[112:115], v[166:169], v[182:185], v[112:115]
	v_mfma_f32_16x16x32_bf16 v[104:107], v[174:177], v[182:185], v[104:107]
	v_mfma_f32_16x16x32_bf16 v[96:99], v[166:169], v[190:193], v[96:99]
	v_mfma_f32_16x16x32_bf16 v[88:91], v[174:177], v[190:193], v[88:91]
	v_mfma_f32_16x16x32_bf16 v[80:83], v[166:169], v[198:201], v[80:83]
	v_mfma_f32_16x16x32_bf16 v[72:75], v[174:177], v[198:201], v[72:75]
	v_mfma_f32_16x16x32_bf16 v[68:71], v[166:169], v[210:213], v[68:71]
	v_mfma_f32_16x16x32_bf16 v[64:67], v[174:177], v[210:213], v[64:67]
	v_mfma_f32_16x16x32_bf16 v[112:115], v[170:173], v[186:189], v[112:115]
	v_mfma_f32_16x16x32_bf16 v[104:107], v[178:181], v[186:189], v[104:107]
	v_mfma_f32_16x16x32_bf16 v[96:99], v[170:173], v[194:197], v[96:99]
	v_mfma_f32_16x16x32_bf16 v[88:91], v[178:181], v[194:197], v[88:91]
	v_mfma_f32_16x16x32_bf16 v[80:83], v[170:173], v[202:205], v[80:83]
	v_mfma_f32_16x16x32_bf16 v[72:75], v[178:181], v[202:205], v[72:75]
	v_mfma_f32_16x16x32_bf16 v[68:71], v[170:173], v[214:217], v[68:71]
	v_mfma_f32_16x16x32_bf16 v[64:67], v[178:181], v[214:217], v[64:67]
	s_setprio 0
	s_barrier
; #define PG8_STAGE(bufoff, gbase, voff) do { _Pragma("unroll") for (int _i = 0; _i < 2; ++_i) \
;         __builtin_amdgcn_global_load_lds((const unsigned*)((const char*)(gbase) + (voff)[_i]), (LAS unsigned*)(lds + (bufoff) + ldsw + _i * 8192), 16, 0, 0); } while (0)
; #define PG8_LDA(dst, b, h) do { _Pragma("unroll") for (int m = 0; m < 4; ++m) _Pragma("unroll") for (int k = 0; k < 2; ++k) dst[m][k] = *(const LAS bf16x8*)(lds + PG8_SA(b, h) + aoff + m * 2048 + k * 1024); } while (0)
; #define PG8_MMA(ai, bj, At, Bt) do { __builtin_amdgcn_s_setprio(1); _Pragma("unroll") for (int m = 0; m < 4; ++m) _Pragma("unroll") for (int n = 0; n < 2; ++n) _Pragma("unroll") for (int k = 0; k < 2; ++k) \
;         acc[ai][bj][m][n] = __builtin_amdgcn_mfma_f32_16x16x32_bf16(Bt[n][k], At[m][k], acc[ai][bj][m][n], 0, 0, 0); __builtin_amdgcn_s_setprio(0); } while (0)
; #define PG8_WAIT_V(n) asm volatile("s_waitcnt vmcnt(" #n ")" ::: "memory")
; #define PG8_WAIT_L(n) asm volatile("s_waitcnt lgkmcnt(" #n ")" ::: "memory")
; #define PG8_BAR __builtin_amdgcn_s_barrier()
; #define PG8_SCHED __builtin_amdgcn_sched_barrier(0)
; template <class Epi, class Sched>
; __device__ __forceinline__ void gemm_phase(LAS unsigned char* lds, const Gemm g, const Sched& S, const Epi& E, const int wave_s) {
;     ...
;             PG8_LDA(At, 1, 1); PG8_STAGE(PG8_SB(1, 0), b3, voffB); PG8_STAGE(PG8_SB(1, 1), b3 + hstepB, voffB); PG8_STAGE(PG8_SA(1, 0), a3, voffA);
;             PG8_WAIT_V(8); PG8_WAIT_L(0); PG8_BAR; PG8_MMA(1, 0, At, B0); PG8_MMA(1, 1, At, B1); PG8_BAR; PG8_SCHED;
;         }
;         if (wr == 0) PG8_BAR;
	s_add_i32 s26, s55, s81
	v_lshl_add_u64 v[206:207], v[206:207], 0, s[12:13]
	s_mov_b32 m0, s26
	ds_read_b128 v[182:185], v153 offset:49152
	ds_read_b128 v[186:189], v153 offset:50176
	ds_read_b128 v[190:193], v153 offset:51200
	ds_read_b128 v[194:197], v153 offset:52224
	ds_read_b128 v[198:201], v153 offset:53248
	ds_read_b128 v[202:205], v153 offset:54272
	ds_read_b128 v[210:213], v153 offset:55296
	ds_read_b128 v[214:217], v153 offset:56320
	global_load_lds_dwordx4 v[206:207], off
	s_add_i32 m0, s26, 0x2000
	s_add_u32 s4, s4, 0x40080
	v_lshl_add_u64 v[206:207], v[218:219], 0, s[12:13]
	s_addc_u32 s5, s5, 0
	s_add_i32 s26, s57, s81
	global_load_lds_dwordx4 v[206:207], off
	s_mov_b32 m0, s26
	v_lshl_add_u64 v[206:207], s[4:5], 0, v[132:133]
	global_load_lds_dwordx4 v[206:207], off
	s_add_i32 m0, s26, 0x2000
	v_lshl_add_u64 v[206:207], s[4:5], 0, v[128:129]
	global_load_lds_dwordx4 v[206:207], off
	s_mov_b32 m0, s41
	v_lshl_add_u64 v[206:207], v[220:221], 0, s[12:13]
	global_load_lds_dwordx4 v[206:207], off
	s_mov_b32 m0, s42
	v_lshl_add_u64 v[206:207], v[222:223], 0, s[12:13]
	global_load_lds_dwordx4 v[206:207], off
	s_waitcnt vmcnt(8) lgkmcnt(0)
	s_barrier
	s_setprio 1
	v_mfma_f32_16x16x32_bf16 v[60:63], v[144:147], v[182:185], v[60:63]
	v_mfma_f32_16x16x32_bf16 v[56:59], v[158:161], v[182:185], v[56:59]
	v_mfma_f32_16x16x32_bf16 v[52:55], v[144:147], v[190:193], v[52:55]
	v_mfma_f32_16x16x32_bf16 v[44:47], v[158:161], v[190:193], v[44:47]
	v_mfma_f32_16x16x32_bf16 v[36:39], v[144:147], v[198:201], v[36:39]
	v_mfma_f32_16x16x32_bf16 v[28:31], v[158:161], v[198:201], v[28:31]
	v_mfma_f32_16x16x32_bf16 v[20:23], v[144:147], v[210:213], v[20:23]
	v_mfma_f32_16x16x32_bf16 v[12:15], v[158:161], v[210:213], v[12:15]
	v_mfma_f32_16x16x32_bf16 v[60:63], v[154:157], v[186:189], v[60:63]
	v_mfma_f32_16x16x32_bf16 v[56:59], v[162:165], v[186:189], v[56:59]
	v_mfma_f32_16x16x32_bf16 v[52:55], v[154:157], v[194:197], v[52:55]
	v_mfma_f32_16x16x32_bf16 v[44:47], v[162:165], v[194:197], v[44:47]
	v_mfma_f32_16x16x32_bf16 v[36:39], v[154:157], v[202:205], v[36:39]
	v_mfma_f32_16x16x32_bf16 v[28:31], v[162:165], v[202:205], v[28:31]
	v_mfma_f32_16x16x32_bf16 v[20:23], v[154:157], v[214:217], v[20:23]
	v_mfma_f32_16x16x32_bf16 v[12:15], v[162:165], v[214:217], v[12:15]
	s_setprio 0
	s_setprio 1
	v_mfma_f32_16x16x32_bf16 v[48:51], v[166:169], v[182:185], v[48:51]
	v_mfma_f32_16x16x32_bf16 v[40:43], v[174:177], v[182:185], v[40:43]
	v_mfma_f32_16x16x32_bf16 v[32:35], v[166:169], v[190:193], v[32:35]
	v_mfma_f32_16x16x32_bf16 v[24:27], v[174:177], v[190:193], v[24:27]
	v_mfma_f32_16x16x32_bf16 v[16:19], v[166:169], v[198:201], v[16:19]
	v_mfma_f32_16x16x32_bf16 v[8:11], v[174:177], v[198:201], v[8:11]
	v_mfma_f32_16x16x32_bf16 v[4:7], v[166:169], v[210:213], v[4:7]
	v_mfma_f32_16x16x32_bf16 v[0:3], v[174:177], v[210:213], v[0:3]
	v_mfma_f32_16x16x32_bf16 v[48:51], v[170:173], v[186:189], v[48:51]
	v_mfma_f32_16x16x32_bf16 v[40:43], v[178:181], v[186:189], v[40:43]
	v_mfma_f32_16x16x32_bf16 v[32:35], v[170:173], v[194:197], v[32:35]
	v_mfma_f32_16x16x32_bf16 v[24:27], v[178:181], v[194:197], v[24:27]
	v_mfma_f32_16x16x32_bf16 v[16:19], v[170:173], v[202:205], v[16:19]
	v_mfma_f32_16x16x32_bf16 v[8:11], v[178:181], v[202:205], v[8:11]
	v_mfma_f32_16x16x32_bf16 v[4:7], v[170:173], v[214:217], v[4:7]
	v_mfma_f32_16x16x32_bf16 v[0:3], v[178:181], v[214:217], v[0:3]
	s_setprio 0
	s_barrier
	s_add_i32 s54, s54, 2
	s_add_u32 s24, s24, 0x100
	s_addc_u32 s25, s25, 0
	s_add_u32 s52, s52, 0x100
	s_addc_u32 s53, s53, 0
	s_cmp_gt_u32 s54, 13
	s_cbranch_scc0 .LBB0_194
	s_and_b64 vcc, exec, s[14:15]
	s_cbranch_vccz .LBB0_197
	s_barrier

; #define PG8_STAGE(bufoff, gbase, voff) do { _Pragma("unroll") for (int _i = 0; _i < 2; ++_i) \
;         __builtin_amdgcn_global_load_lds((const unsigned*)((const char*)(gbase) + (voff)[_i]), (LAS unsigned*)(lds + (bufoff) + ldsw + _i * 8192), 16, 0, 0); } while (0)
; #define PG8_LDA(dst, b, h) do { _Pragma("unroll") for (int m = 0; m < 4; ++m) _Pragma("unroll") for (int k = 0; k < 2; ++k) dst[m][k] = *(const LAS bf16x8*)(lds + PG8_SA(b, h) + aoff + m * 2048 + k * 1024); } while (0)
; #define PG8_LDB(dst, b, h) do { _Pragma("unroll") for (int n = 0; n < 2; ++n) _Pragma("unroll") for (int k = 0; k < 2; ++k) dst[n][k] = *(const LAS bf16x8*)(lds + PG8_SB(b, h) + boff + n * 2048 + k * 1024); } while (0)
; #define PG8_MMA(ai, bj, At, Bt) do { __builtin_amdgcn_s_setprio(1); _Pragma("unroll") for (int m = 0; m < 4; ++m) _Pragma("unroll") for (int n = 0; n < 2; ++n) _Pragma("unroll") for (int k = 0; k < 2; ++k) \
;         acc[ai][bj][m][n] = __builtin_amdgcn_mfma_f32_16x16x32_bf16(Bt[n][k], At[m][k], acc[ai][bj][m][n], 0, 0, 0); __builtin_amdgcn_s_setprio(0); } while (0)
; #define PG8_WAIT_V(n) asm volatile("s_waitcnt vmcnt(" #n ")" ::: "memory")
; #define PG8_WAIT_L(n) asm volatile("s_waitcnt lgkmcnt(" #n ")" ::: "memory")
; #define PG8_BAR __builtin_amdgcn_s_barrier()
; #define PG8_SCHED __builtin_amdgcn_sched_barrier(0)
; template <class Epi, class Sched>
; __device__ __forceinline__ void gemm_phase(LAS unsigned char* lds, const Gemm g, const Sched& S, const Epi& E, const int wave_s) {
;     ...
;             PG8_LDB(B0, 0, 0); PG8_LDB(B1, 0, 1); PG8_SCHED; PG8_LDA(At, 0, 0); PG8_STAGE(PG8_SA(1, 1), a1 + hstepA, voffA);
;             PG8_WAIT_V(8); PG8_WAIT_L(0); PG8_BAR; PG8_MMA(0, 0, At, B0); PG8_MMA(0, 1, At, B1); PG8_BAR; PG8_SCHED;
;             PG8_LDA(At, 0, 1); PG8_STAGE(PG8_SB(0, 0), b2, voffB); PG8_STAGE(PG8_SB(0, 1), b2 + hstepB, voffB); PG8_STAGE(PG8_SA(0, 0), a2, voffA);
;             PG8_WAIT_V(8); PG8_WAIT_L(0); PG8_BAR; PG8_MMA(1, 0, At, B0); PG8_MMA(1, 1, At, B1); PG8_BAR; PG8_SCHED;
.LBB0_375:
	ds_read_b128 v[158:161], v155
	ds_read_b128 v[162:165], v155 offset:1024
	ds_read_b128 v[166:169], v155 offset:2048
	ds_read_b128 v[170:173], v155 offset:3072
	ds_read_b128 v[174:177], v156
	ds_read_b128 v[178:181], v156 offset:1024
	ds_read_b128 v[182:185], v156 offset:2048
	ds_read_b128 v[186:189], v156 offset:3072
	s_add_u32 s4, s22, 0x100
	s_addc_u32 s5, s23, 0
	s_cmp_eq_u32 s48, 2
	s_cselect_b32 s25, s19, s5
	s_cselect_b32 s24, s18, s4
	s_cselect_b32 s9, s21, s47
	s_cselect_b32 s8, s20, s46
	v_lshl_add_u64 v[150:151], s[22:23], 0, v[142:143]
	s_add_i32 m0, s27, 0xc000
	ds_read_b128 v[190:193], v157
	ds_read_b128 v[194:197], v157 offset:1024
	ds_read_b128 v[198:201], v157 offset:2048
	ds_read_b128 v[202:205], v157 offset:3072
	ds_read_b128 v[210:213], v157 offset:4096
	ds_read_b128 v[214:217], v157 offset:5120
	ds_read_b128 v[218:221], v157 offset:6144
	ds_read_b128 v[222:225], v157 offset:7168
	global_load_lds_dwordx4 v[150:151], off
	s_add_i32 m0, s27, 0xe000
	v_lshl_add_u64 v[150:151], s[22:23], 0, v[144:145]
	global_load_lds_dwordx4 v[150:151], off
	s_waitcnt vmcnt(8) lgkmcnt(0)
	s_barrier
	s_setprio 1
	v_mfma_f32_16x16x32_bf16 v[124:127], v[158:161], v[190:193], v[124:127]
	v_mfma_f32_16x16x32_bf16 v[120:123], v[166:169], v[190:193], v[120:123]
	v_mfma_f32_16x16x32_bf16 v[108:111], v[158:161], v[198:201], v[108:111]
	v_mfma_f32_16x16x32_bf16 v[104:107], v[166:169], v[198:201], v[104:107]
	v_mfma_f32_16x16x32_bf16 v[92:95], v[158:161], v[210:213], v[92:95]
	v_mfma_f32_16x16x32_bf16 v[88:91], v[166:169], v[210:213], v[88:91]
	v_mfma_f32_16x16x32_bf16 v[76:79], v[158:161], v[218:221], v[76:79]
	v_mfma_f32_16x16x32_bf16 v[72:75], v[166:169], v[218:221], v[72:75]
	v_mfma_f32_16x16x32_bf16 v[124:127], v[162:165], v[194:197], v[124:127]
	v_mfma_f32_16x16x32_bf16 v[120:123], v[170:173], v[194:197], v[120:123]
	v_mfma_f32_16x16x32_bf16 v[108:111], v[162:165], v[202:205], v[108:111]
	v_mfma_f32_16x16x32_bf16 v[104:107], v[170:173], v[202:205], v[104:107]
	v_mfma_f32_16x16x32_bf16 v[92:95], v[162:165], v[214:217], v[92:95]
	v_mfma_f32_16x16x32_bf16 v[88:91], v[170:173], v[214:217], v[88:91]
	v_mfma_f32_16x16x32_bf16 v[76:79], v[162:165], v[222:225], v[76:79]
	v_mfma_f32_16x16x32_bf16 v[72:75], v[170:173], v[222:225], v[72:75]
	s_setprio 0
	s_setprio 1
	v_mfma_f32_16x16x32_bf16 v[116:119], v[174:177], v[190:193], v[116:119]
	v_mfma_f32_16x16x32_bf16 v[112:115], v[182:185], v[190:193], v[112:115]
	v_mfma_f32_16x16x32_bf16 v[100:103], v[174:177], v[198:201], v[100:103]
	v_mfma_f32_16x16x32_bf16 v[96:99], v[182:185], v[198:201], v[96:99]
	v_mfma_f32_16x16x32_bf16 v[84:87], v[174:177], v[210:213], v[84:87]
	v_mfma_f32_16x16x32_bf16 v[80:83], v[182:185], v[210:213], v[80:83]
	v_mfma_f32_16x16x32_bf16 v[68:71], v[174:177], v[218:221], v[68:71]
	v_mfma_f32_16x16x32_bf16 v[64:67], v[182:185], v[218:221], v[64:67]
	v_mfma_f32_16x16x32_bf16 v[116:119], v[178:181], v[194:197], v[116:119]
	v_mfma_f32_16x16x32_bf16 v[112:115], v[186:189], v[194:197], v[112:115]
	v_mfma_f32_16x16x32_bf16 v[100:103], v[178:181], v[202:205], v[100:103]
	v_mfma_f32_16x16x32_bf16 v[96:99], v[186:189], v[202:205], v[96:99]
	v_mfma_f32_16x16x32_bf16 v[84:87], v[178:181], v[214:217], v[84:87]
	v_mfma_f32_16x16x32_bf16 v[80:83], v[186:189], v[214:217], v[80:83]
	v_mfma_f32_16x16x32_bf16 v[68:71], v[178:181], v[222:225], v[68:71]
	v_mfma_f32_16x16x32_bf16 v[64:67], v[186:189], v[222:225], v[64:67]
	s_setprio 0
	s_barrier
	s_add_i32 s22, s39, s81
	v_lshl_add_u64 v[150:151], s[8:9], 0, v[130:131]
	s_mov_b32 m0, s22
	ds_read_b128 v[190:193], v157 offset:16384
	ds_read_b128 v[194:197], v157 offset:17408
	ds_read_b128 v[198:201], v157 offset:18432
	ds_read_b128 v[202:205], v157 offset:19456
	ds_read_b128 v[210:213], v157 offset:20480
	ds_read_b128 v[214:217], v157 offset:21504
	ds_read_b128 v[218:221], v157 offset:22528
	ds_read_b128 v[222:225], v157 offset:23552
	global_load_lds_dwordx4 v[150:151], off
	s_add_i32 m0, s22, 0x2000
	s_add_u32 s22, s8, 0x18000
	v_lshl_add_u64 v[206:207], s[8:9], 0, v[134:135]
	s_addc_u32 s23, s9, 0
	s_add_i32 s49, s40, s81
	global_load_lds_dwordx4 v[206:207], off
	v_lshl_add_u64 v[226:227], s[22:23], 0, v[130:131]
	s_mov_b32 m0, s49
	v_lshl_add_u64 v[228:229], s[24:25], 0, v[132:133]
	global_load_lds_dwordx4 v[226:227], off
	s_add_i32 m0, s49, 0x2000
	v_lshl_add_u64 v[226:227], s[22:23], 0, v[134:135]
	global_load_lds_dwordx4 v[226:227], off
	s_mov_b32 m0, s27
	v_lshl_add_u64 v[226:227], s[24:25], 0, v[128:129]
	global_load_lds_dwordx4 v[226:227], off
	s_mov_b32 m0, s28
	s_nop 0
	global_load_lds_dwordx4 v[228:229], off
	s_waitcnt vmcnt(8) lgkmcnt(0)
	s_barrier
; #define PG8_STAGE(bufoff, gbase, voff) do { _Pragma("unroll") for (int _i = 0; _i < 2; ++_i) \
;         __builtin_amdgcn_global_load_lds((const unsigned*)((const char*)(gbase) + (voff)[_i]), (LAS unsigned*)(lds + (bufoff) + ldsw + _i * 8192), 16, 0, 0); } while (0)
; #define PG8_LDA(dst, b, h) do { _Pragma("unroll") for (int m = 0; m < 4; ++m) _Pragma("unroll") for (int k = 0; k < 2; ++k) dst[m][k] = *(const LAS bf16x8*)(lds + PG8_SA(b, h) + aoff + m * 2048 + k * 1024); } while (0)
; #define PG8_LDB(dst, b, h) do { _Pragma("unroll") for (int n = 0; n < 2; ++n) _Pragma("unroll") for (int k = 0; k < 2; ++k) dst[n][k] = *(const LAS bf16x8*)(lds + PG8_SB(b, h) + boff + n * 2048 + k * 1024); } while (0)
; #define PG8_MMA(ai, bj, At, Bt) do { __builtin_amdgcn_s_setprio(1); _Pragma("unroll") for (int m = 0; m < 4; ++m) _Pragma("unroll") for (int n = 0; n < 2; ++n) _Pragma("unroll") for (int k = 0; k < 2; ++k) \
;         acc[ai][bj][m][n] = __builtin_amdgcn_mfma_f32_16x16x32_bf16(Bt[n][k], At[m][k], acc[ai][bj][m][n], 0, 0, 0); __builtin_amdgcn_s_setprio(0); } while (0)
; #define PG8_WAIT_V(n) asm volatile("s_waitcnt vmcnt(" #n ")" ::: "memory")
; #define PG8_WAIT_L(n) asm volatile("s_waitcnt lgkmcnt(" #n ")" ::: "memory")
; #define PG8_BAR __builtin_amdgcn_s_barrier()
; #define PG8_SCHED __builtin_amdgcn_sched_barrier(0)
; template <class Epi, class Sched>
; __device__ __forceinline__ void gemm_phase(LAS unsigned char* lds, const Gemm g, const Sched& S, const Epi& E, const int wave_s) {
;     ...
;             PG8_WAIT_V(8); PG8_WAIT_L(0); PG8_BAR; PG8_MMA(1, 0, At, B0); PG8_MMA(1, 1, At, B1); PG8_BAR; PG8_SCHED;
;             PG8_LDB(B0, 1, 0); PG8_LDB(B1, 1, 1); PG8_SCHED; PG8_LDA(At, 1, 0); PG8_STAGE(PG8_SA(0, 1), a2 + hstepA, voffA);
;             PG8_WAIT_V(8); PG8_WAIT_L(0); PG8_BAR; PG8_MMA(0, 0, At, B0); PG8_MMA(0, 1, At, B1); PG8_BAR; PG8_SCHED;
	s_setprio 1
	v_mfma_f32_16x16x32_bf16 v[60:63], v[158:161], v[190:193], v[60:63]
	v_mfma_f32_16x16x32_bf16 v[56:59], v[166:169], v[190:193], v[56:59]
	v_mfma_f32_16x16x32_bf16 v[44:47], v[158:161], v[198:201], v[44:47]
	v_mfma_f32_16x16x32_bf16 v[40:43], v[166:169], v[198:201], v[40:43]
	v_mfma_f32_16x16x32_bf16 v[28:31], v[158:161], v[210:213], v[28:31]
	v_mfma_f32_16x16x32_bf16 v[24:27], v[166:169], v[210:213], v[24:27]
	v_mfma_f32_16x16x32_bf16 v[12:15], v[158:161], v[218:221], v[12:15]
	v_mfma_f32_16x16x32_bf16 v[8:11], v[166:169], v[218:221], v[8:11]
	v_mfma_f32_16x16x32_bf16 v[60:63], v[162:165], v[194:197], v[60:63]
	v_mfma_f32_16x16x32_bf16 v[56:59], v[170:173], v[194:197], v[56:59]
	v_mfma_f32_16x16x32_bf16 v[44:47], v[162:165], v[202:205], v[44:47]
	v_mfma_f32_16x16x32_bf16 v[40:43], v[170:173], v[202:205], v[40:43]
	v_mfma_f32_16x16x32_bf16 v[28:31], v[162:165], v[214:217], v[28:31]
	v_mfma_f32_16x16x32_bf16 v[24:27], v[170:173], v[214:217], v[24:27]
	v_mfma_f32_16x16x32_bf16 v[12:15], v[162:165], v[222:225], v[12:15]
	v_mfma_f32_16x16x32_bf16 v[8:11], v[170:173], v[222:225], v[8:11]
	s_setprio 0
	s_setprio 1
	v_mfma_f32_16x16x32_bf16 v[52:55], v[174:177], v[190:193], v[52:55]
	v_mfma_f32_16x16x32_bf16 v[48:51], v[182:185], v[190:193], v[48:51]
	v_mfma_f32_16x16x32_bf16 v[36:39], v[174:177], v[198:201], v[36:39]
	v_mfma_f32_16x16x32_bf16 v[32:35], v[182:185], v[198:201], v[32:35]
	v_mfma_f32_16x16x32_bf16 v[20:23], v[174:177], v[210:213], v[20:23]
	v_mfma_f32_16x16x32_bf16 v[16:19], v[182:185], v[210:213], v[16:19]
	v_mfma_f32_16x16x32_bf16 v[4:7], v[174:177], v[218:221], v[4:7]
	v_mfma_f32_16x16x32_bf16 v[0:3], v[182:185], v[218:221], v[0:3]
	v_mfma_f32_16x16x32_bf16 v[52:55], v[178:181], v[194:197], v[52:55]
	v_mfma_f32_16x16x32_bf16 v[48:51], v[186:189], v[194:197], v[48:51]
	v_mfma_f32_16x16x32_bf16 v[36:39], v[178:181], v[202:205], v[36:39]
	v_mfma_f32_16x16x32_bf16 v[32:35], v[186:189], v[202:205], v[32:35]
	v_mfma_f32_16x16x32_bf16 v[20:23], v[178:181], v[214:217], v[20:23]
	v_mfma_f32_16x16x32_bf16 v[16:19], v[186:189], v[214:217], v[16:19]
	v_mfma_f32_16x16x32_bf16 v[4:7], v[178:181], v[222:225], v[4:7]
	v_mfma_f32_16x16x32_bf16 v[0:3], v[186:189], v[222:225], v[0:3]
	s_setprio 0
	s_barrier
	s_add_i32 s49, 0, 0x18000
	v_add_u32_e32 v136, s49, v153
	s_add_i32 s50, 0, 0x1c000
	ds_read_b128 v[158:161], v136
	ds_read_b128 v[162:165], v136 offset:1024
	ds_read_b128 v[166:169], v136 offset:2048
	ds_read_b128 v[170:173], v136 offset:3072
	v_add_u32_e32 v136, s50, v153
	ds_read_b128 v[174:177], v136
	ds_read_b128 v[178:181], v136 offset:1024
	ds_read_b128 v[182:185], v136 offset:2048
	ds_read_b128 v[186:189], v136 offset:3072
	s_add_u32 s22, s24, 0xf0000
	s_addc_u32 s23, s25, 0
	s_mov_b32 m0, s29
	v_lshl_add_u64 v[230:231], s[22:23], 0, v[128:129]
	ds_read_b128 v[190:193], v157 offset:32768
	ds_read_b128 v[194:197], v157 offset:33792
	ds_read_b128 v[198:201], v157 offset:34816
	ds_read_b128 v[202:205], v157 offset:35840
	ds_read_b128 v[210:213], v157 offset:36864
	ds_read_b128 v[214:217], v157 offset:37888
	ds_read_b128 v[218:221], v157 offset:38912
	ds_read_b128 v[222:225], v157 offset:39936
	global_load_lds_dwordx4 v[230:231], off
	s_mov_b32 m0, s30
	v_lshl_add_u64 v[230:231], s[22:23], 0, v[132:133]
	global_load_lds_dwordx4 v[230:231], off
	s_waitcnt vmcnt(8) lgkmcnt(0)
	s_barrier
	s_setprio 1
	v_mfma_f32_16x16x32_bf16 v[124:127], v[158:161], v[190:193], v[124:127]
	v_mfma_f32_16x16x32_bf16 v[120:123], v[166:169], v[190:193], v[120:123]
	v_mfma_f32_16x16x32_bf16 v[108:111], v[158:161], v[198:201], v[108:111]
	v_mfma_f32_16x16x32_bf16 v[104:107], v[166:169], v[198:201], v[104:107]
	v_mfma_f32_16x16x32_bf16 v[92:95], v[158:161], v[210:213], v[92:95]
	v_mfma_f32_16x16x32_bf16 v[88:91], v[166:169], v[210:213], v[88:91]
	v_mfma_f32_16x16x32_bf16 v[76:79], v[158:161], v[218:221], v[76:79]
	v_mfma_f32_16x16x32_bf16 v[72:75], v[166:169], v[218:221], v[72:75]
	v_mfma_f32_16x16x32_bf16 v[124:127], v[162:165], v[194:197], v[124:127]
	v_mfma_f32_16x16x32_bf16 v[120:123], v[170:173], v[194:197], v[120:123]
	v_mfma_f32_16x16x32_bf16 v[108:111], v[162:165], v[202:205], v[108:111]
	v_mfma_f32_16x16x32_bf16 v[104:107], v[170:173], v[202:205], v[104:107]
	v_mfma_f32_16x16x32_bf16 v[92:95], v[162:165], v[214:217], v[92:95]
	v_mfma_f32_16x16x32_bf16 v[88:91], v[170:173], v[214:217], v[88:91]
	v_mfma_f32_16x16x32_bf16 v[76:79], v[162:165], v[222:225], v[76:79]
	v_mfma_f32_16x16x32_bf16 v[72:75], v[170:173], v[222:225], v[72:75]
	s_setprio 0
	s_setprio 1
	v_mfma_f32_16x16x32_bf16 v[116:119], v[174:177], v[190:193], v[116:119]
	v_mfma_f32_16x16x32_bf16 v[112:115], v[182:185], v[190:193], v[112:115]
	v_mfma_f32_16x16x32_bf16 v[100:103], v[174:177], v[198:201], v[100:103]
	v_mfma_f32_16x16x32_bf16 v[96:99], v[182:185], v[198:201], v[96:99]
	v_mfma_f32_16x16x32_bf16 v[84:87], v[174:177], v[210:213], v[84:87]
	v_mfma_f32_16x16x32_bf16 v[80:83], v[182:185], v[210:213], v[80:83]
	v_mfma_f32_16x16x32_bf16 v[68:71], v[174:177], v[218:221], v[68:71]
	v_mfma_f32_16x16x32_bf16 v[64:67], v[182:185], v[218:221], v[64:67]
	v_mfma_f32_16x16x32_bf16 v[116:119], v[178:181], v[194:197], v[116:119]
	v_mfma_f32_16x16x32_bf16 v[112:115], v[186:189], v[194:197], v[112:115]
	v_mfma_f32_16x16x32_bf16 v[100:103], v[178:181], v[202:205], v[100:103]
	v_mfma_f32_16x16x32_bf16 v[96:99], v[186:189], v[202:205], v[96:99]
	v_mfma_f32_16x16x32_bf16 v[84:87], v[178:181], v[214:217], v[84:87]
	v_mfma_f32_16x16x32_bf16 v[80:83], v[186:189], v[214:217], v[80:83]
	v_mfma_f32_16x16x32_bf16 v[68:71], v[178:181], v[222:225], v[68:71]
	v_mfma_f32_16x16x32_bf16 v[64:67], v[186:189], v[222:225], v[64:67]
	s_setprio 0
	s_barrier
; #define PG8_STAGE(bufoff, gbase, voff) do { _Pragma("unroll") for (int _i = 0; _i < 2; ++_i) \
;         __builtin_amdgcn_global_load_lds((const unsigned*)((const char*)(gbase) + (voff)[_i]), (LAS unsigned*)(lds + (bufoff) + ldsw + _i * 8192), 16, 0, 0); } while (0)
; #define PG8_LDA(dst, b, h) do { _Pragma("unroll") for (int m = 0; m < 4; ++m) _Pragma("unroll") for (int k = 0; k < 2; ++k) dst[m][k] = *(const LAS bf16x8*)(lds + PG8_SA(b, h) + aoff + m * 2048 + k * 1024); } while (0)
; #define PG8_MMA(ai, bj, At, Bt) do { __builtin_amdgcn_s_setprio(1); _Pragma("unroll") for (int m = 0; m < 4; ++m) _Pragma("unroll") for (int n = 0; n < 2; ++n) _Pragma("unroll") for (int k = 0; k < 2; ++k) \
;         acc[ai][bj][m][n] = __builtin_amdgcn_mfma_f32_16x16x32_bf16(Bt[n][k], At[m][k], acc[ai][bj][m][n], 0, 0, 0); __builtin_amdgcn_s_setprio(0); } while (0)
; #define PG8_WAIT_V(n) asm volatile("s_waitcnt vmcnt(" #n ")" ::: "memory")
; #define PG8_WAIT_L(n) asm volatile("s_waitcnt lgkmcnt(" #n ")" ::: "memory")
; #define PG8_BAR __builtin_amdgcn_s_barrier()
; #define PG8_SCHED __builtin_amdgcn_sched_barrier(0)
; template <class Epi, class Sched>
; __device__ __forceinline__ void gemm_phase(LAS unsigned char* lds, const Gemm g, const Sched& S, const Epi& E, const int wave_s) {
;     ...
;             PG8_LDA(At, 1, 1); PG8_STAGE(PG8_SB(1, 0), b3, voffB); PG8_STAGE(PG8_SB(1, 1), b3 + hstepB, voffB); PG8_STAGE(PG8_SA(1, 0), a3, voffA);
;             PG8_WAIT_V(8); PG8_WAIT_L(0); PG8_BAR; PG8_MMA(1, 0, At, B0); PG8_MMA(1, 1, At, B1); PG8_BAR; PG8_SCHED;
;         }
;         if (wr == 0) PG8_BAR;
	s_add_i32 s22, s49, s81
	v_lshl_add_u64 v[150:151], v[150:151], 0, s[14:15]
	s_mov_b32 m0, s22
	ds_read_b128 v[190:193], v157 offset:49152
	ds_read_b128 v[194:197], v157 offset:50176
	ds_read_b128 v[198:201], v157 offset:51200
	ds_read_b128 v[202:205], v157 offset:52224
	ds_read_b128 v[210:213], v157 offset:53248
	ds_read_b128 v[214:217], v157 offset:54272
	ds_read_b128 v[218:221], v157 offset:55296
	ds_read_b128 v[222:225], v157 offset:56320
	global_load_lds_dwordx4 v[150:151], off
	s_add_i32 m0, s22, 0x2000
	s_add_u32 s8, s8, 0x18080
	v_lshl_add_u64 v[150:151], v[206:207], 0, s[14:15]
	s_addc_u32 s9, s9, 0
	s_add_i32 s22, s50, s81
	global_load_lds_dwordx4 v[150:151], off
	s_mov_b32 m0, s22
	v_lshl_add_u64 v[150:151], s[8:9], 0, v[130:131]
	global_load_lds_dwordx4 v[150:151], off
	s_add_i32 m0, s22, 0x2000
	v_lshl_add_u64 v[150:151], s[8:9], 0, v[134:135]
	global_load_lds_dwordx4 v[150:151], off
	s_mov_b32 m0, s33
	v_lshl_add_u64 v[150:151], v[226:227], 0, s[14:15]
	global_load_lds_dwordx4 v[150:151], off
	s_mov_b32 m0, s34
	v_lshl_add_u64 v[150:151], v[228:229], 0, s[14:15]
	global_load_lds_dwordx4 v[150:151], off
	s_waitcnt vmcnt(8) lgkmcnt(0)
	s_barrier
	s_setprio 1
	v_mfma_f32_16x16x32_bf16 v[60:63], v[158:161], v[190:193], v[60:63]
	v_mfma_f32_16x16x32_bf16 v[56:59], v[166:169], v[190:193], v[56:59]
	v_mfma_f32_16x16x32_bf16 v[44:47], v[158:161], v[198:201], v[44:47]
	v_mfma_f32_16x16x32_bf16 v[40:43], v[166:169], v[198:201], v[40:43]
	v_mfma_f32_16x16x32_bf16 v[28:31], v[158:161], v[210:213], v[28:31]
	v_mfma_f32_16x16x32_bf16 v[24:27], v[166:169], v[210:213], v[24:27]
	v_mfma_f32_16x16x32_bf16 v[12:15], v[158:161], v[218:221], v[12:15]
	v_mfma_f32_16x16x32_bf16 v[8:11], v[166:169], v[218:221], v[8:11]
	v_mfma_f32_16x16x32_bf16 v[60:63], v[162:165], v[194:197], v[60:63]
	v_mfma_f32_16x16x32_bf16 v[56:59], v[170:173], v[194:197], v[56:59]
	v_mfma_f32_16x16x32_bf16 v[44:47], v[162:165], v[202:205], v[44:47]
	v_mfma_f32_16x16x32_bf16 v[40:43], v[170:173], v[202:205], v[40:43]
	v_mfma_f32_16x16x32_bf16 v[28:31], v[162:165], v[214:217], v[28:31]
	v_mfma_f32_16x16x32_bf16 v[24:27], v[170:173], v[214:217], v[24:27]
	v_mfma_f32_16x16x32_bf16 v[12:15], v[162:165], v[222:225], v[12:15]
	v_mfma_f32_16x16x32_bf16 v[8:11], v[170:173], v[222:225], v[8:11]
	s_setprio 0
	s_setprio 1
	v_mfma_f32_16x16x32_bf16 v[52:55], v[174:177], v[190:193], v[52:55]
	v_mfma_f32_16x16x32_bf16 v[48:51], v[182:185], v[190:193], v[48:51]
	v_mfma_f32_16x16x32_bf16 v[36:39], v[174:177], v[198:201], v[36:39]
	v_mfma_f32_16x16x32_bf16 v[32:35], v[182:185], v[198:201], v[32:35]
	v_mfma_f32_16x16x32_bf16 v[20:23], v[174:177], v[210:213], v[20:23]
	v_mfma_f32_16x16x32_bf16 v[16:19], v[182:185], v[210:213], v[16:19]
	v_mfma_f32_16x16x32_bf16 v[4:7], v[174:177], v[218:221], v[4:7]
	v_mfma_f32_16x16x32_bf16 v[0:3], v[182:185], v[218:221], v[0:3]
	v_mfma_f32_16x16x32_bf16 v[52:55], v[178:181], v[194:197], v[52:55]
	v_mfma_f32_16x16x32_bf16 v[48:51], v[186:189], v[194:197], v[48:51]
	v_mfma_f32_16x16x32_bf16 v[36:39], v[178:181], v[202:205], v[36:39]
	v_mfma_f32_16x16x32_bf16 v[32:35], v[186:189], v[202:205], v[32:35]
	v_mfma_f32_16x16x32_bf16 v[20:23], v[178:181], v[214:217], v[20:23]
	v_mfma_f32_16x16x32_bf16 v[16:19], v[186:189], v[214:217], v[16:19]
	v_mfma_f32_16x16x32_bf16 v[4:7], v[178:181], v[222:225], v[4:7]
	v_mfma_f32_16x16x32_bf16 v[0:3], v[186:189], v[222:225], v[0:3]
	s_setprio 0
	s_barrier
	s_add_i32 s48, s48, 2
	s_add_u32 s46, s46, 0x100
	s_addc_u32 s47, s47, 0
	s_cmp_gt_u32 s48, 3
	s_mov_b64 s[22:23], s[4:5]
	s_cbranch_scc0 .LBB0_375
	s_and_b64 vcc, exec, s[16:17]
	s_cbranch_vccz .LBB0_378
	s_barrier

; #define PG8_STAGE(bufoff, gbase, voff) do { _Pragma("unroll") for (int _i = 0; _i < 2; ++_i) \
;         __builtin_amdgcn_global_load_lds((const unsigned*)((const char*)(gbase) + (voff)[_i]), (LAS unsigned*)(lds + (bufoff) + ldsw + _i * 8192), 16, 0, 0); } while (0)
; #define PG8_LDA(dst, b, h) do { _Pragma("unroll") for (int m = 0; m < 4; ++m) _Pragma("unroll") for (int k = 0; k < 2; ++k) dst[m][k] = *(const LAS bf16x8*)(lds + PG8_SA(b, h) + aoff + m * 2048 + k * 1024); } while (0)
; #define PG8_LDB(dst, b, h) do { _Pragma("unroll") for (int n = 0; n < 2; ++n) _Pragma("unroll") for (int k = 0; k < 2; ++k) dst[n][k] = *(const LAS bf16x8*)(lds + PG8_SB(b, h) + boff + n * 2048 + k * 1024); } while (0)
; #define PG8_MMA(ai, bj, At, Bt) do { __builtin_amdgcn_s_setprio(1); _Pragma("unroll") for (int m = 0; m < 4; ++m) _Pragma("unroll") for (int n = 0; n < 2; ++n) _Pragma("unroll") for (int k = 0; k < 2; ++k) \
;         acc[ai][bj][m][n] = __builtin_amdgcn_mfma_f32_16x16x32_bf16(Bt[n][k], At[m][k], acc[ai][bj][m][n], 0, 0, 0); __builtin_amdgcn_s_setprio(0); } while (0)
; #define PG8_WAIT_V(n) asm volatile("s_waitcnt vmcnt(" #n ")" ::: "memory")
; #define PG8_WAIT_L(n) asm volatile("s_waitcnt lgkmcnt(" #n ")" ::: "memory")
; #define PG8_BAR __builtin_amdgcn_s_barrier()
; #define PG8_SCHED __builtin_amdgcn_sched_barrier(0)
; template <class Epi, class Sched>
; __device__ __forceinline__ void gemm_phase(LAS unsigned char* lds, const Gemm g, const Sched& S, const Epi& E, const int wave_s) {
;     ...
;             PG8_LDB(B0, 0, 0); PG8_LDB(B1, 0, 1); PG8_SCHED; PG8_LDA(At, 0, 0); PG8_STAGE(PG8_SA(1, 1), a1 + hstepA, voffA);
;             PG8_WAIT_V(8); PG8_WAIT_L(0); PG8_BAR; PG8_MMA(0, 0, At, B0); PG8_MMA(0, 1, At, B1); PG8_BAR; PG8_SCHED;
;             PG8_LDA(At, 0, 1); PG8_STAGE(PG8_SB(0, 0), b2, voffB); PG8_STAGE(PG8_SB(0, 1), b2 + hstepB, voffB); PG8_STAGE(PG8_SA(0, 0), a2, voffA);
;             PG8_WAIT_V(8); PG8_WAIT_L(0); PG8_BAR; PG8_MMA(1, 0, At, B0); PG8_MMA(1, 1, At, B1); PG8_BAR; PG8_SCHED;
.LBB0_417:
	s_add_u32 s39, s36, s38
	s_addc_u32 s44, s37, 0
	s_add_u32 s42, s39, 0x100
	s_addc_u32 s43, s44, 0
	s_and_b64 s[40:41], s[4:5], exec
	s_cselect_b32 s41, s29, s43
	s_cselect_b32 s40, s28, s42
	s_add_u32 s38, s34, s38
	s_addc_u32 s42, s35, 0
	s_add_u32 s38, s38, 0x100
	s_addc_u32 s42, s42, 0
	s_and_b64 s[4:5], s[4:5], exec
	s_cselect_b32 s43, s27, s42
	s_cselect_b32 s42, s68, s38
	s_add_u32 s46, s39, 0xf0080
	ds_read_b128 v[148:151], v145
	ds_read_b128 v[152:155], v145 offset:1024
	ds_read_b128 v[156:159], v145 offset:2048
	ds_read_b128 v[160:163], v145 offset:3072
	ds_read_b128 v[164:167], v146
	ds_read_b128 v[168:171], v146 offset:1024
	ds_read_b128 v[172:175], v146 offset:2048
	ds_read_b128 v[176:179], v146 offset:3072
	s_addc_u32 s47, s44, 0
	s_add_i32 s76, s59, s81
	s_add_i32 m0, s49, 0xc000
	s_add_i32 s79, s49, 0xe000
	s_add_i32 s73, s76, 0x2000
	s_add_u32 s44, s42, 0x10000
	s_addc_u32 s45, s43, 0
	s_add_i32 s75, s60, s81
	s_add_i32 s74, s75, 0x2000
	s_add_i32 s72, 0, 0x18000
	s_add_i32 s71, 0, 0x1c000
	s_add_u32 s38, s40, 0xf0000
	s_addc_u32 s39, s41, 0
	s_add_i32 s70, s72, s81
	s_add_i32 s69, s70, 0x2000
	s_add_u32 s4, s42, 0x10080
	s_addc_u32 s5, s43, 0
	s_add_i32 s78, s71, s81
	s_add_i32 s77, s78, 0x2000
	v_lshl_add_u64 v[140:141], s[46:47], 0, v[128:129]
	ds_read_b128 v[180:183], v147
	ds_read_b128 v[184:187], v147 offset:1024
	ds_read_b128 v[188:191], v147 offset:2048
	ds_read_b128 v[192:195], v147 offset:3072
	ds_read_b128 v[196:199], v147 offset:4096
	ds_read_b128 v[200:203], v147 offset:5120
	ds_read_b128 v[204:207], v147 offset:6144
	ds_read_b128 v[210:213], v147 offset:7168
	global_load_lds_dwordx4 v[140:141], off
	s_mov_b32 m0, s79
	v_lshl_add_u64 v[140:141], s[46:47], 0, v[132:133]
	global_load_lds_dwordx4 v[140:141], off
	s_waitcnt vmcnt(8) lgkmcnt(0)
	s_barrier
	s_setprio 1
	v_mfma_f32_16x16x32_bf16 v[124:127], v[148:151], v[180:183], v[124:127]
	v_mfma_f32_16x16x32_bf16 v[120:123], v[156:159], v[180:183], v[120:123]
	v_mfma_f32_16x16x32_bf16 v[116:119], v[148:151], v[188:191], v[116:119]
	v_mfma_f32_16x16x32_bf16 v[108:111], v[156:159], v[188:191], v[108:111]
	v_mfma_f32_16x16x32_bf16 v[100:103], v[148:151], v[196:199], v[100:103]
	v_mfma_f32_16x16x32_bf16 v[92:95], v[156:159], v[196:199], v[92:95]
	v_mfma_f32_16x16x32_bf16 v[84:87], v[148:151], v[204:207], v[84:87]
	v_mfma_f32_16x16x32_bf16 v[76:79], v[156:159], v[204:207], v[76:79]
	v_mfma_f32_16x16x32_bf16 v[124:127], v[152:155], v[184:187], v[124:127]
	v_mfma_f32_16x16x32_bf16 v[120:123], v[160:163], v[184:187], v[120:123]
	v_mfma_f32_16x16x32_bf16 v[116:119], v[152:155], v[192:195], v[116:119]
	v_mfma_f32_16x16x32_bf16 v[108:111], v[160:163], v[192:195], v[108:111]
	v_mfma_f32_16x16x32_bf16 v[100:103], v[152:155], v[200:203], v[100:103]
	v_mfma_f32_16x16x32_bf16 v[92:95], v[160:163], v[200:203], v[92:95]
	v_mfma_f32_16x16x32_bf16 v[84:87], v[152:155], v[210:213], v[84:87]
	v_mfma_f32_16x16x32_bf16 v[76:79], v[160:163], v[210:213], v[76:79]
	s_setprio 0
	s_setprio 1
	v_mfma_f32_16x16x32_bf16 v[112:115], v[164:167], v[180:183], v[112:115]
	v_mfma_f32_16x16x32_bf16 v[104:107], v[172:175], v[180:183], v[104:107]
	v_mfma_f32_16x16x32_bf16 v[96:99], v[164:167], v[188:191], v[96:99]
	v_mfma_f32_16x16x32_bf16 v[88:91], v[172:175], v[188:191], v[88:91]
	v_mfma_f32_16x16x32_bf16 v[80:83], v[164:167], v[196:199], v[80:83]
	v_mfma_f32_16x16x32_bf16 v[72:75], v[172:175], v[196:199], v[72:75]
	v_mfma_f32_16x16x32_bf16 v[68:71], v[164:167], v[204:207], v[68:71]
	v_mfma_f32_16x16x32_bf16 v[64:67], v[172:175], v[204:207], v[64:67]
	v_mfma_f32_16x16x32_bf16 v[112:115], v[168:171], v[184:187], v[112:115]
	v_mfma_f32_16x16x32_bf16 v[104:107], v[176:179], v[184:187], v[104:107]
	v_mfma_f32_16x16x32_bf16 v[96:99], v[168:171], v[192:195], v[96:99]
	v_mfma_f32_16x16x32_bf16 v[88:91], v[176:179], v[192:195], v[88:91]
	v_mfma_f32_16x16x32_bf16 v[80:83], v[168:171], v[200:203], v[80:83]
	v_mfma_f32_16x16x32_bf16 v[72:75], v[176:179], v[200:203], v[72:75]
	v_mfma_f32_16x16x32_bf16 v[68:71], v[168:171], v[210:213], v[68:71]
	v_mfma_f32_16x16x32_bf16 v[64:67], v[176:179], v[210:213], v[64:67]
	s_setprio 0
	s_barrier
	s_mov_b32 m0, s76
	v_lshl_add_u64 v[140:141], s[42:43], 0, v[130:131]
	ds_read_b128 v[180:183], v147 offset:16384
	ds_read_b128 v[184:187], v147 offset:17408
	ds_read_b128 v[188:191], v147 offset:18432
	ds_read_b128 v[192:195], v147 offset:19456
	ds_read_b128 v[196:199], v147 offset:20480
	ds_read_b128 v[200:203], v147 offset:21504
	ds_read_b128 v[204:207], v147 offset:22528
	ds_read_b128 v[210:213], v147 offset:23552
	global_load_lds_dwordx4 v[140:141], off
	v_lshl_add_u64 v[214:215], s[42:43], 0, v[134:135]
	s_mov_b32 m0, s73
	v_lshl_add_u64 v[216:217], s[44:45], 0, v[130:131]
	global_load_lds_dwordx4 v[214:215], off
	s_mov_b32 m0, s75
	v_lshl_add_u64 v[218:219], s[40:41], 0, v[132:133]
	global_load_lds_dwordx4 v[216:217], off
	s_mov_b32 m0, s74
	v_lshl_add_u64 v[216:217], s[44:45], 0, v[134:135]
	global_load_lds_dwordx4 v[216:217], off
	s_mov_b32 m0, s49
	v_lshl_add_u64 v[216:217], s[40:41], 0, v[128:129]
	global_load_lds_dwordx4 v[216:217], off
	s_mov_b32 m0, s50
	s_nop 0
	global_load_lds_dwordx4 v[218:219], off
	s_waitcnt vmcnt(8) lgkmcnt(0)
	s_barrier
; #define PG8_STAGE(bufoff, gbase, voff) do { _Pragma("unroll") for (int _i = 0; _i < 2; ++_i) \
;         __builtin_amdgcn_global_load_lds((const unsigned*)((const char*)(gbase) + (voff)[_i]), (LAS unsigned*)(lds + (bufoff) + ldsw + _i * 8192), 16, 0, 0); } while (0)
; #define PG8_LDA(dst, b, h) do { _Pragma("unroll") for (int m = 0; m < 4; ++m) _Pragma("unroll") for (int k = 0; k < 2; ++k) dst[m][k] = *(const LAS bf16x8*)(lds + PG8_SA(b, h) + aoff + m * 2048 + k * 1024); } while (0)
; #define PG8_LDB(dst, b, h) do { _Pragma("unroll") for (int n = 0; n < 2; ++n) _Pragma("unroll") for (int k = 0; k < 2; ++k) dst[n][k] = *(const LAS bf16x8*)(lds + PG8_SB(b, h) + boff + n * 2048 + k * 1024); } while (0)
; #define PG8_MMA(ai, bj, At, Bt) do { __builtin_amdgcn_s_setprio(1); _Pragma("unroll") for (int m = 0; m < 4; ++m) _Pragma("unroll") for (int n = 0; n < 2; ++n) _Pragma("unroll") for (int k = 0; k < 2; ++k) \
;         acc[ai][bj][m][n] = __builtin_amdgcn_mfma_f32_16x16x32_bf16(Bt[n][k], At[m][k], acc[ai][bj][m][n], 0, 0, 0); __builtin_amdgcn_s_setprio(0); } while (0)
; #define PG8_WAIT_V(n) asm volatile("s_waitcnt vmcnt(" #n ")" ::: "memory")
; #define PG8_WAIT_L(n) asm volatile("s_waitcnt lgkmcnt(" #n ")" ::: "memory")
; #define PG8_BAR __builtin_amdgcn_s_barrier()
; #define PG8_SCHED __builtin_amdgcn_sched_barrier(0)
; template <class Epi, class Sched>
; __device__ __forceinline__ void gemm_phase(LAS unsigned char* lds, const Gemm g, const Sched& S, const Epi& E, const int wave_s) {
;     ...
;             PG8_WAIT_V(8); PG8_WAIT_L(0); PG8_BAR; PG8_MMA(1, 0, At, B0); PG8_MMA(1, 1, At, B1); PG8_BAR; PG8_SCHED;
;             PG8_LDB(B0, 1, 0); PG8_LDB(B1, 1, 1); PG8_SCHED; PG8_LDA(At, 1, 0); PG8_STAGE(PG8_SA(0, 1), a2 + hstepA, voffA);
;             PG8_WAIT_V(8); PG8_WAIT_L(0); PG8_BAR; PG8_MMA(0, 0, At, B0); PG8_MMA(0, 1, At, B1); PG8_BAR; PG8_SCHED;
	s_setprio 1
	v_mfma_f32_16x16x32_bf16 v[60:63], v[148:151], v[180:183], v[60:63]
	v_mfma_f32_16x16x32_bf16 v[56:59], v[156:159], v[180:183], v[56:59]
	v_mfma_f32_16x16x32_bf16 v[52:55], v[148:151], v[188:191], v[52:55]
	v_mfma_f32_16x16x32_bf16 v[44:47], v[156:159], v[188:191], v[44:47]
	v_mfma_f32_16x16x32_bf16 v[36:39], v[148:151], v[196:199], v[36:39]
	v_mfma_f32_16x16x32_bf16 v[28:31], v[156:159], v[196:199], v[28:31]
	v_mfma_f32_16x16x32_bf16 v[20:23], v[148:151], v[204:207], v[20:23]
	v_mfma_f32_16x16x32_bf16 v[12:15], v[156:159], v[204:207], v[12:15]
	v_mfma_f32_16x16x32_bf16 v[60:63], v[152:155], v[184:187], v[60:63]
	v_mfma_f32_16x16x32_bf16 v[56:59], v[160:163], v[184:187], v[56:59]
	v_mfma_f32_16x16x32_bf16 v[52:55], v[152:155], v[192:195], v[52:55]
	v_mfma_f32_16x16x32_bf16 v[44:47], v[160:163], v[192:195], v[44:47]
	v_mfma_f32_16x16x32_bf16 v[36:39], v[152:155], v[200:203], v[36:39]
	v_mfma_f32_16x16x32_bf16 v[28:31], v[160:163], v[200:203], v[28:31]
	v_mfma_f32_16x16x32_bf16 v[20:23], v[152:155], v[210:213], v[20:23]
	v_mfma_f32_16x16x32_bf16 v[12:15], v[160:163], v[210:213], v[12:15]
	s_setprio 0
	s_setprio 1
	v_mfma_f32_16x16x32_bf16 v[48:51], v[164:167], v[180:183], v[48:51]
	v_mfma_f32_16x16x32_bf16 v[40:43], v[172:175], v[180:183], v[40:43]
	v_mfma_f32_16x16x32_bf16 v[32:35], v[164:167], v[188:191], v[32:35]
	v_mfma_f32_16x16x32_bf16 v[24:27], v[172:175], v[188:191], v[24:27]
	v_mfma_f32_16x16x32_bf16 v[16:19], v[164:167], v[196:199], v[16:19]
	v_mfma_f32_16x16x32_bf16 v[8:11], v[172:175], v[196:199], v[8:11]
	v_mfma_f32_16x16x32_bf16 v[4:7], v[164:167], v[204:207], v[4:7]
	v_mfma_f32_16x16x32_bf16 v[0:3], v[172:175], v[204:207], v[0:3]
	v_mfma_f32_16x16x32_bf16 v[48:51], v[168:171], v[184:187], v[48:51]
	v_mfma_f32_16x16x32_bf16 v[40:43], v[176:179], v[184:187], v[40:43]
	v_mfma_f32_16x16x32_bf16 v[32:35], v[168:171], v[192:195], v[32:35]
	v_mfma_f32_16x16x32_bf16 v[24:27], v[176:179], v[192:195], v[24:27]
	v_mfma_f32_16x16x32_bf16 v[16:19], v[168:171], v[200:203], v[16:19]
	v_mfma_f32_16x16x32_bf16 v[8:11], v[176:179], v[200:203], v[8:11]
	v_mfma_f32_16x16x32_bf16 v[4:7], v[168:171], v[210:213], v[4:7]
	v_mfma_f32_16x16x32_bf16 v[0:3], v[176:179], v[210:213], v[0:3]
	s_setprio 0
	s_barrier
	v_add_u32_e32 v160, s72, v143
	v_add_u32_e32 v176, s71, v143
	ds_read_b128 v[148:151], v160
	ds_read_b128 v[152:155], v160 offset:1024
	ds_read_b128 v[156:159], v160 offset:2048
	ds_read_b128 v[160:163], v160 offset:3072
	ds_read_b128 v[164:167], v176
	ds_read_b128 v[168:171], v176 offset:1024
	ds_read_b128 v[172:175], v176 offset:2048
	ds_read_b128 v[176:179], v176 offset:3072
	s_mov_b32 m0, s51
	v_lshl_add_u64 v[220:221], s[38:39], 0, v[128:129]
	ds_read_b128 v[180:183], v147 offset:32768
	ds_read_b128 v[184:187], v147 offset:33792
	ds_read_b128 v[188:191], v147 offset:34816
	ds_read_b128 v[192:195], v147 offset:35840
	ds_read_b128 v[196:199], v147 offset:36864
	ds_read_b128 v[200:203], v147 offset:37888
	ds_read_b128 v[204:207], v147 offset:38912
	ds_read_b128 v[210:213], v147 offset:39936
	global_load_lds_dwordx4 v[220:221], off
	s_mov_b32 m0, s52
	v_lshl_add_u64 v[220:221], s[38:39], 0, v[132:133]
	global_load_lds_dwordx4 v[220:221], off
	s_waitcnt vmcnt(8) lgkmcnt(0)
	s_barrier
	s_setprio 1
	v_mfma_f32_16x16x32_bf16 v[124:127], v[148:151], v[180:183], v[124:127]
	v_mfma_f32_16x16x32_bf16 v[120:123], v[156:159], v[180:183], v[120:123]
	v_mfma_f32_16x16x32_bf16 v[116:119], v[148:151], v[188:191], v[116:119]
	v_mfma_f32_16x16x32_bf16 v[108:111], v[156:159], v[188:191], v[108:111]
	v_mfma_f32_16x16x32_bf16 v[100:103], v[148:151], v[196:199], v[100:103]
	v_mfma_f32_16x16x32_bf16 v[92:95], v[156:159], v[196:199], v[92:95]
	v_mfma_f32_16x16x32_bf16 v[84:87], v[148:151], v[204:207], v[84:87]
	v_mfma_f32_16x16x32_bf16 v[76:79], v[156:159], v[204:207], v[76:79]
	v_mfma_f32_16x16x32_bf16 v[124:127], v[152:155], v[184:187], v[124:127]
	v_mfma_f32_16x16x32_bf16 v[120:123], v[160:163], v[184:187], v[120:123]
	v_mfma_f32_16x16x32_bf16 v[116:119], v[152:155], v[192:195], v[116:119]
	v_mfma_f32_16x16x32_bf16 v[108:111], v[160:163], v[192:195], v[108:111]
	v_mfma_f32_16x16x32_bf16 v[100:103], v[152:155], v[200:203], v[100:103]
	v_mfma_f32_16x16x32_bf16 v[92:95], v[160:163], v[200:203], v[92:95]
	v_mfma_f32_16x16x32_bf16 v[84:87], v[152:155], v[210:213], v[84:87]
	v_mfma_f32_16x16x32_bf16 v[76:79], v[160:163], v[210:213], v[76:79]
	s_setprio 0
	s_setprio 1
	v_mfma_f32_16x16x32_bf16 v[112:115], v[164:167], v[180:183], v[112:115]
	v_mfma_f32_16x16x32_bf16 v[104:107], v[172:175], v[180:183], v[104:107]
	v_mfma_f32_16x16x32_bf16 v[96:99], v[164:167], v[188:191], v[96:99]
	v_mfma_f32_16x16x32_bf16 v[88:91], v[172:175], v[188:191], v[88:91]
	v_mfma_f32_16x16x32_bf16 v[80:83], v[164:167], v[196:199], v[80:83]
	v_mfma_f32_16x16x32_bf16 v[72:75], v[172:175], v[196:199], v[72:75]
	v_mfma_f32_16x16x32_bf16 v[68:71], v[164:167], v[204:207], v[68:71]
	v_mfma_f32_16x16x32_bf16 v[64:67], v[172:175], v[204:207], v[64:67]
	v_mfma_f32_16x16x32_bf16 v[112:115], v[168:171], v[184:187], v[112:115]
	v_mfma_f32_16x16x32_bf16 v[104:107], v[176:179], v[184:187], v[104:107]
	v_mfma_f32_16x16x32_bf16 v[96:99], v[168:171], v[192:195], v[96:99]
	v_mfma_f32_16x16x32_bf16 v[88:91], v[176:179], v[192:195], v[88:91]
	v_mfma_f32_16x16x32_bf16 v[80:83], v[168:171], v[200:203], v[80:83]
	v_mfma_f32_16x16x32_bf16 v[72:75], v[176:179], v[200:203], v[72:75]
	v_mfma_f32_16x16x32_bf16 v[68:71], v[168:171], v[210:213], v[68:71]
	v_mfma_f32_16x16x32_bf16 v[64:67], v[176:179], v[210:213], v[64:67]
	s_setprio 0
	s_barrier
; #define PG8_STAGE(bufoff, gbase, voff) do { _Pragma("unroll") for (int _i = 0; _i < 2; ++_i) \
;         __builtin_amdgcn_global_load_lds((const unsigned*)((const char*)(gbase) + (voff)[_i]), (LAS unsigned*)(lds + (bufoff) + ldsw + _i * 8192), 16, 0, 0); } while (0)
; #define PG8_LDA(dst, b, h) do { _Pragma("unroll") for (int m = 0; m < 4; ++m) _Pragma("unroll") for (int k = 0; k < 2; ++k) dst[m][k] = *(const LAS bf16x8*)(lds + PG8_SA(b, h) + aoff + m * 2048 + k * 1024); } while (0)
; #define PG8_MMA(ai, bj, At, Bt) do { __builtin_amdgcn_s_setprio(1); _Pragma("unroll") for (int m = 0; m < 4; ++m) _Pragma("unroll") for (int n = 0; n < 2; ++n) _Pragma("unroll") for (int k = 0; k < 2; ++k) \
;         acc[ai][bj][m][n] = __builtin_amdgcn_mfma_f32_16x16x32_bf16(Bt[n][k], At[m][k], acc[ai][bj][m][n], 0, 0, 0); __builtin_amdgcn_s_setprio(0); } while (0)
; #define PG8_WAIT_V(n) asm volatile("s_waitcnt vmcnt(" #n ")" ::: "memory")
; #define PG8_WAIT_L(n) asm volatile("s_waitcnt lgkmcnt(" #n ")" ::: "memory")
; #define PG8_BAR __builtin_amdgcn_s_barrier()
; #define PG8_SCHED __builtin_amdgcn_sched_barrier(0)
; template <class Epi, class Sched>
; __device__ __forceinline__ void gemm_phase(LAS unsigned char* lds, const Gemm g, const Sched& S, const Epi& E, const int wave_s) {
;     ...
;             PG8_LDA(At, 1, 1); PG8_STAGE(PG8_SB(1, 0), b3, voffB); PG8_STAGE(PG8_SB(1, 1), b3 + hstepB, voffB); PG8_STAGE(PG8_SA(1, 0), a3, voffA);
;             PG8_WAIT_V(8); PG8_WAIT_L(0); PG8_BAR; PG8_MMA(1, 0, At, B0); PG8_MMA(1, 1, At, B1); PG8_BAR; PG8_SCHED;
;         }
;         if (wr == 0) PG8_BAR;
	s_mov_b32 m0, s70
	v_lshl_add_u64 v[140:141], v[140:141], 0, s[14:15]
	ds_read_b128 v[180:183], v147 offset:49152
	ds_read_b128 v[184:187], v147 offset:50176
	ds_read_b128 v[188:191], v147 offset:51200
	ds_read_b128 v[192:195], v147 offset:52224
	ds_read_b128 v[196:199], v147 offset:53248
	ds_read_b128 v[200:203], v147 offset:54272
	ds_read_b128 v[204:207], v147 offset:55296
	ds_read_b128 v[210:213], v147 offset:56320
	global_load_lds_dwordx4 v[140:141], off
	s_mov_b32 m0, s69
	v_lshl_add_u64 v[140:141], v[214:215], 0, s[14:15]
	global_load_lds_dwordx4 v[140:141], off
	s_mov_b32 m0, s78
	v_lshl_add_u64 v[140:141], s[4:5], 0, v[130:131]
	global_load_lds_dwordx4 v[140:141], off
	s_mov_b32 m0, s77
	v_lshl_add_u64 v[140:141], s[4:5], 0, v[134:135]
	global_load_lds_dwordx4 v[140:141], off
	s_mov_b32 m0, s54
	v_lshl_add_u64 v[140:141], v[216:217], 0, s[14:15]
	global_load_lds_dwordx4 v[140:141], off
	s_mov_b32 m0, s55
	v_lshl_add_u64 v[140:141], v[218:219], 0, s[14:15]
	global_load_lds_dwordx4 v[140:141], off
	s_waitcnt vmcnt(8) lgkmcnt(0)
	s_barrier
	s_setprio 1
	v_mfma_f32_16x16x32_bf16 v[60:63], v[148:151], v[180:183], v[60:63]
	v_mfma_f32_16x16x32_bf16 v[56:59], v[156:159], v[180:183], v[56:59]
	v_mfma_f32_16x16x32_bf16 v[52:55], v[148:151], v[188:191], v[52:55]
	v_mfma_f32_16x16x32_bf16 v[44:47], v[156:159], v[188:191], v[44:47]
	v_mfma_f32_16x16x32_bf16 v[36:39], v[148:151], v[196:199], v[36:39]
	v_mfma_f32_16x16x32_bf16 v[28:31], v[156:159], v[196:199], v[28:31]
	v_mfma_f32_16x16x32_bf16 v[20:23], v[148:151], v[204:207], v[20:23]
	v_mfma_f32_16x16x32_bf16 v[12:15], v[156:159], v[204:207], v[12:15]
	v_mfma_f32_16x16x32_bf16 v[60:63], v[152:155], v[184:187], v[60:63]
	v_mfma_f32_16x16x32_bf16 v[56:59], v[160:163], v[184:187], v[56:59]
	v_mfma_f32_16x16x32_bf16 v[52:55], v[152:155], v[192:195], v[52:55]
	v_mfma_f32_16x16x32_bf16 v[44:47], v[160:163], v[192:195], v[44:47]
	v_mfma_f32_16x16x32_bf16 v[36:39], v[152:155], v[200:203], v[36:39]
	v_mfma_f32_16x16x32_bf16 v[28:31], v[160:163], v[200:203], v[28:31]
	v_mfma_f32_16x16x32_bf16 v[20:23], v[152:155], v[210:213], v[20:23]
	v_mfma_f32_16x16x32_bf16 v[12:15], v[160:163], v[210:213], v[12:15]
	s_setprio 0
	s_setprio 1
	v_mfma_f32_16x16x32_bf16 v[48:51], v[164:167], v[180:183], v[48:51]
	v_mfma_f32_16x16x32_bf16 v[40:43], v[172:175], v[180:183], v[40:43]
	v_mfma_f32_16x16x32_bf16 v[32:35], v[164:167], v[188:191], v[32:35]
	v_mfma_f32_16x16x32_bf16 v[24:27], v[172:175], v[188:191], v[24:27]
	v_mfma_f32_16x16x32_bf16 v[16:19], v[164:167], v[196:199], v[16:19]
	v_mfma_f32_16x16x32_bf16 v[8:11], v[172:175], v[196:199], v[8:11]
	v_mfma_f32_16x16x32_bf16 v[4:7], v[164:167], v[204:207], v[4:7]
	v_mfma_f32_16x16x32_bf16 v[0:3], v[172:175], v[204:207], v[0:3]
	v_mfma_f32_16x16x32_bf16 v[48:51], v[168:171], v[184:187], v[48:51]
	v_mfma_f32_16x16x32_bf16 v[40:43], v[176:179], v[184:187], v[40:43]
	v_mfma_f32_16x16x32_bf16 v[32:35], v[168:171], v[192:195], v[32:35]
	v_mfma_f32_16x16x32_bf16 v[24:27], v[176:179], v[192:195], v[24:27]
	v_mfma_f32_16x16x32_bf16 v[16:19], v[168:171], v[200:203], v[16:19]
	v_mfma_f32_16x16x32_bf16 v[8:11], v[176:179], v[200:203], v[8:11]
	v_mfma_f32_16x16x32_bf16 v[4:7], v[168:171], v[210:213], v[4:7]
	v_mfma_f32_16x16x32_bf16 v[0:3], v[176:179], v[210:213], v[0:3]
	s_setprio 0
	s_barrier
	s_movk_i32 s38, 0x100
	s_andn2_b64 vcc, exec, s[8:9]
	s_mov_b64 s[4:5], -1
	s_mov_b64 s[8:9], 0
	s_cbranch_vccz .LBB0_417
	s_and_b64 vcc, exec, s[16:17]
	s_cbranch_vccz .LBB0_420
	s_barrier

; #define PG8_STAGE(bufoff, gbase, voff) do { _Pragma("unroll") for (int _i = 0; _i < 2; ++_i) \
;         __builtin_amdgcn_global_load_lds((const unsigned*)((const char*)(gbase) + (voff)[_i]), (LAS unsigned*)(lds + (bufoff) + ldsw + _i * 8192), 16, 0, 0); } while (0)
; #define PG8_LDA(dst, b, h) do { _Pragma("unroll") for (int m = 0; m < 4; ++m) _Pragma("unroll") for (int k = 0; k < 2; ++k) dst[m][k] = *(const LAS bf16x8*)(lds + PG8_SA(b, h) + aoff + m * 2048 + k * 1024); } while (0)
; #define PG8_LDB(dst, b, h) do { _Pragma("unroll") for (int n = 0; n < 2; ++n) _Pragma("unroll") for (int k = 0; k < 2; ++k) dst[n][k] = *(const LAS bf16x8*)(lds + PG8_SB(b, h) + boff + n * 2048 + k * 1024); } while (0)
; #define PG8_MMA(ai, bj, At, Bt) do { __builtin_amdgcn_s_setprio(1); _Pragma("unroll") for (int m = 0; m < 4; ++m) _Pragma("unroll") for (int n = 0; n < 2; ++n) _Pragma("unroll") for (int k = 0; k < 2; ++k) \
;         acc[ai][bj][m][n] = __builtin_amdgcn_mfma_f32_16x16x32_bf16(Bt[n][k], At[m][k], acc[ai][bj][m][n], 0, 0, 0); __builtin_amdgcn_s_setprio(0); } while (0)
; #define PG8_WAIT_V(n) asm volatile("s_waitcnt vmcnt(" #n ")" ::: "memory")
; #define PG8_WAIT_L(n) asm volatile("s_waitcnt lgkmcnt(" #n ")" ::: "memory")
; #define PG8_BAR __builtin_amdgcn_s_barrier()
; #define PG8_SCHED __builtin_amdgcn_sched_barrier(0)
; template <class Epi, class Sched>
; __device__ __forceinline__ void gemm_phase(LAS unsigned char* lds, const Gemm g, const Sched& S, const Epi& E, const int wave_s) {
;     ...
;             const bool last = (t == nt - 2);
;             const char* a1 = cA + (size_t)(t + 1) * kstep;
;             const char* a2 = last ? nA : cA + (size_t)(t + 2) * kstep; const char* b2 = last ? nB : cB + (size_t)(t + 2) * kstep;
;             const char* a3 = a2 + kstep; const char* b3 = b2 + kstep;
;             PG8_LDB(B0, 0, 0); PG8_LDB(B1, 0, 1); PG8_SCHED; PG8_LDA(At, 0, 0); PG8_STAGE(PG8_SA(1, 1), a1 + hstepA, voffA);
;             PG8_WAIT_V(8); PG8_WAIT_L(0); PG8_BAR; PG8_MMA(0, 0, At, B0); PG8_MMA(0, 1, At, B1); PG8_BAR; PG8_SCHED;
;             PG8_LDA(At, 0, 1); PG8_STAGE(PG8_SB(0, 0), b2, voffB); PG8_STAGE(PG8_SB(0, 1), b2 + hstepB, voffB); PG8_STAGE(PG8_SA(0, 0), a2, voffA);
;             PG8_WAIT_V(8); PG8_WAIT_L(0); PG8_BAR; PG8_MMA(1, 0, At, B0); PG8_MMA(1, 1, At, B1); PG8_BAR; PG8_SCHED;
.LBB0_860:
	ds_read_b128 v[100:103], v212
	ds_read_b128 v[108:111], v212 offset:1024
	ds_read_b128 v[136:139], v212 offset:2048
	ds_read_b128 v[140:143], v212 offset:3072
	ds_read_b128 v[144:147], v213
	ds_read_b128 v[148:151], v213 offset:1024
	ds_read_b128 v[152:155], v213 offset:2048
	ds_read_b128 v[156:159], v213 offset:3072
	s_add_u32 s4, s40, 0xfffc0080
	s_addc_u32 s5, s41, -1
	s_cmp_eq_u32 s54, 12
	s_cselect_b32 s43, s9, s5
	s_cselect_b32 s42, s27, s4
	s_cselect_b32 s5, s29, s53
	s_cselect_b32 s4, s31, s39
	v_lshl_add_u64 v[206:207], s[40:41], 0, v[178:179]
	s_add_i32 m0, s3, 0xc000
	ds_read_b128 v[160:163], v214
	ds_read_b128 v[164:167], v214 offset:1024
	ds_read_b128 v[186:189], v214 offset:2048
	ds_read_b128 v[190:193], v214 offset:3072
	ds_read_b128 v[194:197], v214 offset:4096
	ds_read_b128 v[198:201], v214 offset:5120
	ds_read_b128 v[202:205], v214 offset:6144
	ds_read_b128 v[216:219], v214 offset:7168
	global_load_lds_dwordx4 v[206:207], off
	s_add_i32 m0, s3, 0xe000
	v_lshl_add_u64 v[206:207], s[40:41], 0, v[180:181]
	global_load_lds_dwordx4 v[206:207], off
	s_waitcnt vmcnt(8) lgkmcnt(0)
	s_barrier
	s_setprio 1
	v_mfma_f32_16x16x32_bf16 v[132:135], v[100:103], v[160:163], v[132:135]
	v_mfma_f32_16x16x32_bf16 v[128:131], v[136:139], v[160:163], v[128:131]
	v_mfma_f32_16x16x32_bf16 v[124:127], v[100:103], v[186:189], v[124:127]
	v_mfma_f32_16x16x32_bf16 v[120:123], v[136:139], v[186:189], v[120:123]
	v_mfma_f32_16x16x32_bf16 v[116:119], v[100:103], v[194:197], v[116:119]
	v_mfma_f32_16x16x32_bf16 v[112:115], v[136:139], v[194:197], v[112:115]
	v_mfma_f32_16x16x32_bf16 v[104:107], v[100:103], v[202:205], v[104:107]
	v_mfma_f32_16x16x32_bf16 v[96:99], v[136:139], v[202:205], v[96:99]
	v_mfma_f32_16x16x32_bf16 v[132:135], v[108:111], v[164:167], v[132:135]
	v_mfma_f32_16x16x32_bf16 v[128:131], v[140:143], v[164:167], v[128:131]
	v_mfma_f32_16x16x32_bf16 v[124:127], v[108:111], v[190:193], v[124:127]
	v_mfma_f32_16x16x32_bf16 v[120:123], v[140:143], v[190:193], v[120:123]
	v_mfma_f32_16x16x32_bf16 v[116:119], v[108:111], v[198:201], v[116:119]
	v_mfma_f32_16x16x32_bf16 v[112:115], v[140:143], v[198:201], v[112:115]
	v_mfma_f32_16x16x32_bf16 v[104:107], v[108:111], v[216:219], v[104:107]
	v_mfma_f32_16x16x32_bf16 v[96:99], v[140:143], v[216:219], v[96:99]
	s_setprio 0
	s_setprio 1
	v_mfma_f32_16x16x32_bf16 v[60:63], v[144:147], v[160:163], v[60:63]
	v_mfma_f32_16x16x32_bf16 v[56:59], v[152:155], v[160:163], v[56:59]
	v_mfma_f32_16x16x32_bf16 v[52:55], v[144:147], v[186:189], v[52:55]
	v_mfma_f32_16x16x32_bf16 v[48:51], v[152:155], v[186:189], v[48:51]
	v_mfma_f32_16x16x32_bf16 v[44:47], v[144:147], v[194:197], v[44:47]
	v_mfma_f32_16x16x32_bf16 v[40:43], v[152:155], v[194:197], v[40:43]
	v_mfma_f32_16x16x32_bf16 v[36:39], v[144:147], v[202:205], v[36:39]
	v_mfma_f32_16x16x32_bf16 v[32:35], v[152:155], v[202:205], v[32:35]
	v_mfma_f32_16x16x32_bf16 v[60:63], v[148:151], v[164:167], v[60:63]
	v_mfma_f32_16x16x32_bf16 v[56:59], v[156:159], v[164:167], v[56:59]
	v_mfma_f32_16x16x32_bf16 v[52:55], v[148:151], v[190:193], v[52:55]
	v_mfma_f32_16x16x32_bf16 v[48:51], v[156:159], v[190:193], v[48:51]
	v_mfma_f32_16x16x32_bf16 v[44:47], v[148:151], v[198:201], v[44:47]
	v_mfma_f32_16x16x32_bf16 v[40:43], v[156:159], v[198:201], v[40:43]
	v_mfma_f32_16x16x32_bf16 v[36:39], v[148:151], v[216:219], v[36:39]
	v_mfma_f32_16x16x32_bf16 v[32:35], v[156:159], v[216:219], v[32:35]
	s_setprio 0
	s_barrier
	s_add_i32 s55, s50, s81
	v_lshl_add_u64 v[206:207], s[4:5], 0, v[170:171]
	s_mov_b32 m0, s55
	ds_read_b128 v[160:163], v214 offset:16384
	ds_read_b128 v[164:167], v214 offset:17408
	ds_read_b128 v[186:189], v214 offset:18432
	ds_read_b128 v[190:193], v214 offset:19456
	ds_read_b128 v[194:197], v214 offset:20480
	ds_read_b128 v[198:201], v214 offset:21504
	ds_read_b128 v[202:205], v214 offset:22528
	ds_read_b128 v[216:219], v214 offset:23552
	global_load_lds_dwordx4 v[206:207], off
	s_add_i32 m0, s55, 0x2000
	s_add_u32 s56, s4, 0x40000
	v_lshl_add_u64 v[220:221], s[4:5], 0, v[174:175]
	s_addc_u32 s57, s5, 0
	s_add_i32 s55, s51, s81
	global_load_lds_dwordx4 v[220:221], off
	v_lshl_add_u64 v[222:223], s[56:57], 0, v[170:171]
	s_mov_b32 m0, s55
	v_lshl_add_u64 v[224:225], s[42:43], 0, v[172:173]
	global_load_lds_dwordx4 v[222:223], off
	s_add_i32 m0, s55, 0x2000
	v_lshl_add_u64 v[222:223], s[56:57], 0, v[174:175]
	global_load_lds_dwordx4 v[222:223], off
	s_mov_b32 m0, s3
	v_lshl_add_u64 v[222:223], s[42:43], 0, v[168:169]
	global_load_lds_dwordx4 v[222:223], off
	s_mov_b32 m0, s33
	s_nop 0
	global_load_lds_dwordx4 v[224:225], off
	s_waitcnt vmcnt(8) lgkmcnt(0)
	s_barrier
; #define PG8_STAGE(bufoff, gbase, voff) do { _Pragma("unroll") for (int _i = 0; _i < 2; ++_i) \
;         __builtin_amdgcn_global_load_lds((const unsigned*)((const char*)(gbase) + (voff)[_i]), (LAS unsigned*)(lds + (bufoff) + ldsw + _i * 8192), 16, 0, 0); } while (0)
; #define PG8_LDA(dst, b, h) do { _Pragma("unroll") for (int m = 0; m < 4; ++m) _Pragma("unroll") for (int k = 0; k < 2; ++k) dst[m][k] = *(const LAS bf16x8*)(lds + PG8_SA(b, h) + aoff + m * 2048 + k * 1024); } while (0)
; #define PG8_LDB(dst, b, h) do { _Pragma("unroll") for (int n = 0; n < 2; ++n) _Pragma("unroll") for (int k = 0; k < 2; ++k) dst[n][k] = *(const LAS bf16x8*)(lds + PG8_SB(b, h) + boff + n * 2048 + k * 1024); } while (0)
; #define PG8_MMA(ai, bj, At, Bt) do { __builtin_amdgcn_s_setprio(1); _Pragma("unroll") for (int m = 0; m < 4; ++m) _Pragma("unroll") for (int n = 0; n < 2; ++n) _Pragma("unroll") for (int k = 0; k < 2; ++k) \
;         acc[ai][bj][m][n] = __builtin_amdgcn_mfma_f32_16x16x32_bf16(Bt[n][k], At[m][k], acc[ai][bj][m][n], 0, 0, 0); __builtin_amdgcn_s_setprio(0); } while (0)
; #define PG8_WAIT_V(n) asm volatile("s_waitcnt vmcnt(" #n ")" ::: "memory")
; #define PG8_WAIT_L(n) asm volatile("s_waitcnt lgkmcnt(" #n ")" ::: "memory")
; #define PG8_BAR __builtin_amdgcn_s_barrier()
; #define PG8_SCHED __builtin_amdgcn_sched_barrier(0)
; template <class Epi, class Sched>
; __device__ __forceinline__ void gemm_phase(LAS unsigned char* lds, const Gemm g, const Sched& S, const Epi& E, const int wave_s) {
;     ...
;             PG8_WAIT_V(8); PG8_WAIT_L(0); PG8_BAR; PG8_MMA(1, 0, At, B0); PG8_MMA(1, 1, At, B1); PG8_BAR; PG8_SCHED;
;             PG8_LDB(B0, 1, 0); PG8_LDB(B1, 1, 1); PG8_SCHED; PG8_LDA(At, 1, 0); PG8_STAGE(PG8_SA(0, 1), a2 + hstepA, voffA);
;             PG8_WAIT_V(8); PG8_WAIT_L(0); PG8_BAR; PG8_MMA(0, 0, At, B0); PG8_MMA(0, 1, At, B1); PG8_BAR; PG8_SCHED;
	s_setprio 1
	v_mfma_f32_16x16x32_bf16 v[92:95], v[100:103], v[160:163], v[92:95]
	v_mfma_f32_16x16x32_bf16 v[88:91], v[136:139], v[160:163], v[88:91]
	v_mfma_f32_16x16x32_bf16 v[84:87], v[100:103], v[186:189], v[84:87]
	v_mfma_f32_16x16x32_bf16 v[80:83], v[136:139], v[186:189], v[80:83]
	v_mfma_f32_16x16x32_bf16 v[76:79], v[100:103], v[194:197], v[76:79]
	v_mfma_f32_16x16x32_bf16 v[72:75], v[136:139], v[194:197], v[72:75]
	v_mfma_f32_16x16x32_bf16 v[68:71], v[100:103], v[202:205], v[68:71]
	v_mfma_f32_16x16x32_bf16 v[64:67], v[136:139], v[202:205], v[64:67]
	v_mfma_f32_16x16x32_bf16 v[92:95], v[108:111], v[164:167], v[92:95]
	v_mfma_f32_16x16x32_bf16 v[88:91], v[140:143], v[164:167], v[88:91]
	v_mfma_f32_16x16x32_bf16 v[84:87], v[108:111], v[190:193], v[84:87]
	v_mfma_f32_16x16x32_bf16 v[80:83], v[140:143], v[190:193], v[80:83]
	v_mfma_f32_16x16x32_bf16 v[76:79], v[108:111], v[198:201], v[76:79]
	v_mfma_f32_16x16x32_bf16 v[72:75], v[140:143], v[198:201], v[72:75]
	v_mfma_f32_16x16x32_bf16 v[68:71], v[108:111], v[216:219], v[68:71]
	v_mfma_f32_16x16x32_bf16 v[64:67], v[140:143], v[216:219], v[64:67]
	s_setprio 0
	s_setprio 1
	v_mfma_f32_16x16x32_bf16 v[28:31], v[144:147], v[160:163], v[28:31]
	v_mfma_f32_16x16x32_bf16 v[24:27], v[152:155], v[160:163], v[24:27]
	v_mfma_f32_16x16x32_bf16 v[20:23], v[144:147], v[186:189], v[20:23]
	v_mfma_f32_16x16x32_bf16 v[16:19], v[152:155], v[186:189], v[16:19]
	v_mfma_f32_16x16x32_bf16 v[12:15], v[144:147], v[194:197], v[12:15]
	v_mfma_f32_16x16x32_bf16 v[8:11], v[152:155], v[194:197], v[8:11]
	v_mfma_f32_16x16x32_bf16 v[4:7], v[144:147], v[202:205], v[4:7]
	v_mfma_f32_16x16x32_bf16 v[0:3], v[152:155], v[202:205], v[0:3]
	v_mfma_f32_16x16x32_bf16 v[28:31], v[148:151], v[164:167], v[28:31]
	v_mfma_f32_16x16x32_bf16 v[24:27], v[156:159], v[164:167], v[24:27]
	v_mfma_f32_16x16x32_bf16 v[20:23], v[148:151], v[190:193], v[20:23]
	v_mfma_f32_16x16x32_bf16 v[16:19], v[156:159], v[190:193], v[16:19]
	v_mfma_f32_16x16x32_bf16 v[12:15], v[148:151], v[198:201], v[12:15]
	v_mfma_f32_16x16x32_bf16 v[8:11], v[156:159], v[198:201], v[8:11]
	v_mfma_f32_16x16x32_bf16 v[4:7], v[148:151], v[216:219], v[4:7]
	v_mfma_f32_16x16x32_bf16 v[0:3], v[156:159], v[216:219], v[0:3]
	s_setprio 0
	s_barrier
	s_add_i32 s55, 0, 0x18000
	s_add_i32 s56, 0, 0x1c000
	v_add_u32_e32 v140, s55, v210
	v_add_u32_e32 v156, s56, v210
	ds_read_b128 v[100:103], v140
	ds_read_b128 v[108:111], v140 offset:1024
	ds_read_b128 v[136:139], v140 offset:2048
	ds_read_b128 v[140:143], v140 offset:3072
	ds_read_b128 v[144:147], v156
	ds_read_b128 v[148:151], v156 offset:1024
	ds_read_b128 v[152:155], v156 offset:2048
	ds_read_b128 v[156:159], v156 offset:3072
	s_add_u32 s42, s42, 0x40000
	s_addc_u32 s43, s43, 0
	s_mov_b32 m0, s44
	v_lshl_add_u64 v[226:227], s[42:43], 0, v[168:169]
	ds_read_b128 v[160:163], v214 offset:32768
	ds_read_b128 v[164:167], v214 offset:33792
	ds_read_b128 v[186:189], v214 offset:34816
	ds_read_b128 v[190:193], v214 offset:35840
	ds_read_b128 v[194:197], v214 offset:36864
	ds_read_b128 v[198:201], v214 offset:37888
	ds_read_b128 v[202:205], v214 offset:38912
	ds_read_b128 v[216:219], v214 offset:39936
	global_load_lds_dwordx4 v[226:227], off
	s_mov_b32 m0, s45
	v_lshl_add_u64 v[226:227], s[42:43], 0, v[172:173]
	global_load_lds_dwordx4 v[226:227], off
	s_waitcnt vmcnt(8) lgkmcnt(0)
	s_barrier
	s_setprio 1
	v_mfma_f32_16x16x32_bf16 v[132:135], v[100:103], v[160:163], v[132:135]
	v_mfma_f32_16x16x32_bf16 v[128:131], v[136:139], v[160:163], v[128:131]
	v_mfma_f32_16x16x32_bf16 v[124:127], v[100:103], v[186:189], v[124:127]
	v_mfma_f32_16x16x32_bf16 v[120:123], v[136:139], v[186:189], v[120:123]
	v_mfma_f32_16x16x32_bf16 v[116:119], v[100:103], v[194:197], v[116:119]
	v_mfma_f32_16x16x32_bf16 v[112:115], v[136:139], v[194:197], v[112:115]
	v_mfma_f32_16x16x32_bf16 v[104:107], v[100:103], v[202:205], v[104:107]
	v_mfma_f32_16x16x32_bf16 v[96:99], v[136:139], v[202:205], v[96:99]
	v_mfma_f32_16x16x32_bf16 v[132:135], v[108:111], v[164:167], v[132:135]
	v_mfma_f32_16x16x32_bf16 v[128:131], v[140:143], v[164:167], v[128:131]
	v_mfma_f32_16x16x32_bf16 v[124:127], v[108:111], v[190:193], v[124:127]
	v_mfma_f32_16x16x32_bf16 v[120:123], v[140:143], v[190:193], v[120:123]
	v_mfma_f32_16x16x32_bf16 v[116:119], v[108:111], v[198:201], v[116:119]
	v_mfma_f32_16x16x32_bf16 v[112:115], v[140:143], v[198:201], v[112:115]
	v_mfma_f32_16x16x32_bf16 v[104:107], v[108:111], v[216:219], v[104:107]
	v_mfma_f32_16x16x32_bf16 v[96:99], v[140:143], v[216:219], v[96:99]
	s_setprio 0
	s_setprio 1
	v_mfma_f32_16x16x32_bf16 v[60:63], v[144:147], v[160:163], v[60:63]
	v_mfma_f32_16x16x32_bf16 v[56:59], v[152:155], v[160:163], v[56:59]
	v_mfma_f32_16x16x32_bf16 v[52:55], v[144:147], v[186:189], v[52:55]
	v_mfma_f32_16x16x32_bf16 v[48:51], v[152:155], v[186:189], v[48:51]
	v_mfma_f32_16x16x32_bf16 v[44:47], v[144:147], v[194:197], v[44:47]
	v_mfma_f32_16x16x32_bf16 v[40:43], v[152:155], v[194:197], v[40:43]
	v_mfma_f32_16x16x32_bf16 v[36:39], v[144:147], v[202:205], v[36:39]
	v_mfma_f32_16x16x32_bf16 v[32:35], v[152:155], v[202:205], v[32:35]
	v_mfma_f32_16x16x32_bf16 v[60:63], v[148:151], v[164:167], v[60:63]
	v_mfma_f32_16x16x32_bf16 v[56:59], v[156:159], v[164:167], v[56:59]
	v_mfma_f32_16x16x32_bf16 v[52:55], v[148:151], v[190:193], v[52:55]
	v_mfma_f32_16x16x32_bf16 v[48:51], v[156:159], v[190:193], v[48:51]
	v_mfma_f32_16x16x32_bf16 v[44:47], v[148:151], v[198:201], v[44:47]
	v_mfma_f32_16x16x32_bf16 v[40:43], v[156:159], v[198:201], v[40:43]
	v_mfma_f32_16x16x32_bf16 v[36:39], v[148:151], v[216:219], v[36:39]
	v_mfma_f32_16x16x32_bf16 v[32:35], v[156:159], v[216:219], v[32:35]
	s_setprio 0
	s_barrier
; #define PG8_STAGE(bufoff, gbase, voff) do { _Pragma("unroll") for (int _i = 0; _i < 2; ++_i) \
;         __builtin_amdgcn_global_load_lds((const unsigned*)((const char*)(gbase) + (voff)[_i]), (LAS unsigned*)(lds + (bufoff) + ldsw + _i * 8192), 16, 0, 0); } while (0)
; #define PG8_LDA(dst, b, h) do { _Pragma("unroll") for (int m = 0; m < 4; ++m) _Pragma("unroll") for (int k = 0; k < 2; ++k) dst[m][k] = *(const LAS bf16x8*)(lds + PG8_SA(b, h) + aoff + m * 2048 + k * 1024); } while (0)
; #define PG8_MMA(ai, bj, At, Bt) do { __builtin_amdgcn_s_setprio(1); _Pragma("unroll") for (int m = 0; m < 4; ++m) _Pragma("unroll") for (int n = 0; n < 2; ++n) _Pragma("unroll") for (int k = 0; k < 2; ++k) \
;         acc[ai][bj][m][n] = __builtin_amdgcn_mfma_f32_16x16x32_bf16(Bt[n][k], At[m][k], acc[ai][bj][m][n], 0, 0, 0); __builtin_amdgcn_s_setprio(0); } while (0)
; #define PG8_WAIT_V(n) asm volatile("s_waitcnt vmcnt(" #n ")" ::: "memory")
; #define PG8_WAIT_L(n) asm volatile("s_waitcnt lgkmcnt(" #n ")" ::: "memory")
; #define PG8_BAR __builtin_amdgcn_s_barrier()
; #define PG8_SCHED __builtin_amdgcn_sched_barrier(0)
; template <class Epi, class Sched>
; __device__ __forceinline__ void gemm_phase(LAS unsigned char* lds, const Gemm g, const Sched& S, const Epi& E, const int wave_s) {
;     ...
;             PG8_LDA(At, 1, 1); PG8_STAGE(PG8_SB(1, 0), b3, voffB); PG8_STAGE(PG8_SB(1, 1), b3 + hstepB, voffB); PG8_STAGE(PG8_SA(1, 0), a3, voffA);
;             PG8_WAIT_V(8); PG8_WAIT_L(0); PG8_BAR; PG8_MMA(1, 0, At, B0); PG8_MMA(1, 1, At, B1); PG8_BAR; PG8_SCHED;
;         }
	s_add_i32 s42, s55, s81
	v_lshl_add_u64 v[206:207], v[206:207], 0, s[22:23]
	s_mov_b32 m0, s42
	ds_read_b128 v[160:163], v214 offset:49152
	ds_read_b128 v[164:167], v214 offset:50176
	ds_read_b128 v[186:189], v214 offset:51200
	ds_read_b128 v[190:193], v214 offset:52224
	ds_read_b128 v[194:197], v214 offset:53248
	ds_read_b128 v[198:201], v214 offset:54272
	ds_read_b128 v[202:205], v214 offset:55296
	ds_read_b128 v[216:219], v214 offset:56320
	global_load_lds_dwordx4 v[206:207], off
	s_add_i32 m0, s42, 0x2000
	s_add_u32 s4, s4, 0x40080
	v_lshl_add_u64 v[206:207], v[220:221], 0, s[22:23]
	s_addc_u32 s5, s5, 0
	s_add_i32 s42, s56, s81
	global_load_lds_dwordx4 v[206:207], off
	s_mov_b32 m0, s42
	v_lshl_add_u64 v[206:207], s[4:5], 0, v[170:171]
	global_load_lds_dwordx4 v[206:207], off
	s_add_i32 m0, s42, 0x2000
	v_lshl_add_u64 v[206:207], s[4:5], 0, v[174:175]
	global_load_lds_dwordx4 v[206:207], off
	s_mov_b32 m0, s47
	v_lshl_add_u64 v[206:207], v[222:223], 0, s[22:23]
	global_load_lds_dwordx4 v[206:207], off
	s_mov_b32 m0, s48
	v_lshl_add_u64 v[206:207], v[224:225], 0, s[22:23]
	global_load_lds_dwordx4 v[206:207], off
	s_waitcnt vmcnt(8) lgkmcnt(0)
	s_barrier
	s_setprio 1
	v_mfma_f32_16x16x32_bf16 v[92:95], v[100:103], v[160:163], v[92:95]
	v_mfma_f32_16x16x32_bf16 v[88:91], v[136:139], v[160:163], v[88:91]
	v_mfma_f32_16x16x32_bf16 v[84:87], v[100:103], v[186:189], v[84:87]
	v_mfma_f32_16x16x32_bf16 v[80:83], v[136:139], v[186:189], v[80:83]
	v_mfma_f32_16x16x32_bf16 v[76:79], v[100:103], v[194:197], v[76:79]
	v_mfma_f32_16x16x32_bf16 v[72:75], v[136:139], v[194:197], v[72:75]
	v_mfma_f32_16x16x32_bf16 v[68:71], v[100:103], v[202:205], v[68:71]
	v_mfma_f32_16x16x32_bf16 v[64:67], v[136:139], v[202:205], v[64:67]
	v_mfma_f32_16x16x32_bf16 v[92:95], v[108:111], v[164:167], v[92:95]
	v_mfma_f32_16x16x32_bf16 v[88:91], v[140:143], v[164:167], v[88:91]
	v_mfma_f32_16x16x32_bf16 v[84:87], v[108:111], v[190:193], v[84:87]
	v_mfma_f32_16x16x32_bf16 v[80:83], v[140:143], v[190:193], v[80:83]
	v_mfma_f32_16x16x32_bf16 v[76:79], v[108:111], v[198:201], v[76:79]
	v_mfma_f32_16x16x32_bf16 v[72:75], v[140:143], v[198:201], v[72:75]
	v_mfma_f32_16x16x32_bf16 v[68:71], v[108:111], v[216:219], v[68:71]
	v_mfma_f32_16x16x32_bf16 v[64:67], v[140:143], v[216:219], v[64:67]
	s_setprio 0
	s_setprio 1
	v_mfma_f32_16x16x32_bf16 v[28:31], v[144:147], v[160:163], v[28:31]
	v_mfma_f32_16x16x32_bf16 v[24:27], v[152:155], v[160:163], v[24:27]
	v_mfma_f32_16x16x32_bf16 v[20:23], v[144:147], v[186:189], v[20:23]
	v_mfma_f32_16x16x32_bf16 v[16:19], v[152:155], v[186:189], v[16:19]
	v_mfma_f32_16x16x32_bf16 v[12:15], v[144:147], v[194:197], v[12:15]
	v_mfma_f32_16x16x32_bf16 v[8:11], v[152:155], v[194:197], v[8:11]
	v_mfma_f32_16x16x32_bf16 v[4:7], v[144:147], v[202:205], v[4:7]
	v_mfma_f32_16x16x32_bf16 v[0:3], v[152:155], v[202:205], v[0:3]
	v_mfma_f32_16x16x32_bf16 v[28:31], v[148:151], v[164:167], v[28:31]
	v_mfma_f32_16x16x32_bf16 v[24:27], v[156:159], v[164:167], v[24:27]
	v_mfma_f32_16x16x32_bf16 v[20:23], v[148:151], v[190:193], v[20:23]
	v_mfma_f32_16x16x32_bf16 v[16:19], v[156:159], v[190:193], v[16:19]
	v_mfma_f32_16x16x32_bf16 v[12:15], v[148:151], v[198:201], v[12:15]
	v_mfma_f32_16x16x32_bf16 v[8:11], v[156:159], v[198:201], v[8:11]
	v_mfma_f32_16x16x32_bf16 v[4:7], v[148:151], v[216:219], v[4:7]
	v_mfma_f32_16x16x32_bf16 v[0:3], v[156:159], v[216:219], v[0:3]
	s_setprio 0
	s_barrier
	s_add_i32 s54, s54, 2
	s_add_u32 s40, s40, 0x100
	s_addc_u32 s41, s41, 0
	s_add_u32 s39, s39, 0x100
	s_addc_u32 s53, s53, 0
	s_cmp_gt_u32 s54, 13
	s_cbranch_scc0 .LBB0_860
	s_and_b64 vcc, exec, s[24:25]
	s_cbranch_vccz .LBB0_863
	s_barrier

; #define PG8_STAGE(bufoff, gbase, voff) do { _Pragma("unroll") for (int _i = 0; _i < 2; ++_i) \
;         __builtin_amdgcn_global_load_lds((const unsigned*)((const char*)(gbase) + (voff)[_i]), (LAS unsigned*)(lds + (bufoff) + ldsw + _i * 8192), 16, 0, 0); } while (0)
; #define PG8_LDA(dst, b, h) do { _Pragma("unroll") for (int m = 0; m < 4; ++m) _Pragma("unroll") for (int k = 0; k < 2; ++k) dst[m][k] = *(const LAS bf16x8*)(lds + PG8_SA(b, h) + aoff + m * 2048 + k * 1024); } while (0)
; #define PG8_LDB(dst, b, h) do { _Pragma("unroll") for (int n = 0; n < 2; ++n) _Pragma("unroll") for (int k = 0; k < 2; ++k) dst[n][k] = *(const LAS bf16x8*)(lds + PG8_SB(b, h) + boff + n * 2048 + k * 1024); } while (0)
; #define PG8_MMA(ai, bj, At, Bt) do { __builtin_amdgcn_s_setprio(1); _Pragma("unroll") for (int m = 0; m < 4; ++m) _Pragma("unroll") for (int n = 0; n < 2; ++n) _Pragma("unroll") for (int k = 0; k < 2; ++k) \
;         acc[ai][bj][m][n] = __builtin_amdgcn_mfma_f32_16x16x32_bf16(Bt[n][k], At[m][k], acc[ai][bj][m][n], 0, 0, 0); __builtin_amdgcn_s_setprio(0); } while (0)
; #define PG8_WAIT_V(n) asm volatile("s_waitcnt vmcnt(" #n ")" ::: "memory")
; #define PG8_WAIT_L(n) asm volatile("s_waitcnt lgkmcnt(" #n ")" ::: "memory")
; #define PG8_BAR __builtin_amdgcn_s_barrier()
; #define PG8_SCHED __builtin_amdgcn_sched_barrier(0)
; template <class Epi, class Sched>
; __device__ __forceinline__ void gemm_phase(LAS unsigned char* lds, const Gemm g, const Sched& S, const Epi& E, const int wave_s) {
;     ...
;             const bool last = (t == nt - 2);
;             const char* a1 = cA + (size_t)(t + 1) * kstep;
;             const char* a2 = last ? nA : cA + (size_t)(t + 2) * kstep; const char* b2 = last ? nB : cB + (size_t)(t + 2) * kstep;
;             const char* a3 = a2 + kstep; const char* b3 = b2 + kstep;
;             PG8_LDB(B0, 0, 0); PG8_LDB(B1, 0, 1); PG8_SCHED; PG8_LDA(At, 0, 0); PG8_STAGE(PG8_SA(1, 1), a1 + hstepA, voffA);
;             PG8_WAIT_V(8); PG8_WAIT_L(0); PG8_BAR; PG8_MMA(0, 0, At, B0); PG8_MMA(0, 1, At, B1); PG8_BAR; PG8_SCHED;
;             PG8_LDA(At, 0, 1); PG8_STAGE(PG8_SB(0, 0), b2, voffB); PG8_STAGE(PG8_SB(0, 1), b2 + hstepB, voffB); PG8_STAGE(PG8_SA(0, 0), a2, voffA);
;             PG8_WAIT_V(8); PG8_WAIT_L(0); PG8_BAR; PG8_MMA(1, 0, At, B0); PG8_MMA(1, 1, At, B1); PG8_BAR; PG8_SCHED;
.LBB0_1024:
	s_add_u32 s48, s64, s46
	s_addc_u32 s49, s65, s47
	s_add_u32 s48, s48, 0x99a5200
	s_addc_u32 s49, s49, 0
	s_add_u32 s73, s70, s46
	s_addc_u32 s74, s71, s47
	s_add_i32 s75, 0, 0x10000
	s_cmpk_eq_i32 s46, 0x700
	s_cselect_b32 s51, s11, s49
	s_cselect_b32 s50, s10, s48
	v_add_u32_e32 v128, s75, v178
	s_cselect_b32 s49, s68, s74
	s_cselect_b32 s48, s69, s73
	s_add_i32 s73, 0, 0x14000
	ds_read_b128 v[170:173], v128
	ds_read_b128 v[182:185], v128 offset:1024
	ds_read_b128 v[186:189], v128 offset:2048
	ds_read_b128 v[190:193], v128 offset:3072
	v_add_u32_e32 v128, s73, v178
	ds_read_b128 v[194:197], v128
	ds_read_b128 v[198:201], v128 offset:1024
	ds_read_b128 v[202:205], v128 offset:2048
	ds_read_b128 v[206:209], v128 offset:3072
	v_lshl_add_u64 v[242:243], v[166:167], 0, s[46:47]
	s_add_i32 m0, s52, 0xc000
	ds_read_b128 v[210:213], v180
	ds_read_b128 v[214:217], v180 offset:1024
	ds_read_b128 v[218:221], v180 offset:2048
	ds_read_b128 v[222:225], v180 offset:3072
	ds_read_b128 v[226:229], v180 offset:4096
	ds_read_b128 v[230:233], v180 offset:5120
	ds_read_b128 v[234:237], v180 offset:6144
	ds_read_b128 v[238:241], v180 offset:7168
	global_load_lds_dwordx4 v[242:243], off
	s_add_i32 m0, s52, 0xe000
	v_lshl_add_u64 v[242:243], v[168:169], 0, s[46:47]
	global_load_lds_dwordx4 v[242:243], off
	s_waitcnt vmcnt(8) lgkmcnt(0)
	s_barrier
	s_setprio 1
	v_mfma_f32_16x16x32_bf16 v[124:127], v[170:173], v[210:213], v[124:127]
	v_mfma_f32_16x16x32_bf16 v[120:123], v[186:189], v[210:213], v[120:123]
	v_mfma_f32_16x16x32_bf16 v[116:119], v[170:173], v[218:221], v[116:119]
	v_mfma_f32_16x16x32_bf16 v[112:115], v[186:189], v[218:221], v[112:115]
	v_mfma_f32_16x16x32_bf16 v[108:111], v[170:173], v[226:229], v[108:111]
	v_mfma_f32_16x16x32_bf16 v[100:103], v[186:189], v[226:229], v[100:103]
	v_mfma_f32_16x16x32_bf16 v[92:95], v[170:173], v[234:237], v[92:95]
	v_mfma_f32_16x16x32_bf16 v[84:87], v[186:189], v[234:237], v[84:87]
	v_mfma_f32_16x16x32_bf16 v[124:127], v[182:185], v[214:217], v[124:127]
	v_mfma_f32_16x16x32_bf16 v[120:123], v[190:193], v[214:217], v[120:123]
	v_mfma_f32_16x16x32_bf16 v[116:119], v[182:185], v[222:225], v[116:119]
	v_mfma_f32_16x16x32_bf16 v[112:115], v[190:193], v[222:225], v[112:115]
	v_mfma_f32_16x16x32_bf16 v[108:111], v[182:185], v[230:233], v[108:111]
	v_mfma_f32_16x16x32_bf16 v[100:103], v[190:193], v[230:233], v[100:103]
	v_mfma_f32_16x16x32_bf16 v[92:95], v[182:185], v[238:241], v[92:95]
	v_mfma_f32_16x16x32_bf16 v[84:87], v[190:193], v[238:241], v[84:87]
	s_setprio 0
	s_setprio 1
	v_mfma_f32_16x16x32_bf16 v[104:107], v[194:197], v[210:213], v[104:107]
	v_mfma_f32_16x16x32_bf16 v[96:99], v[202:205], v[210:213], v[96:99]
	v_mfma_f32_16x16x32_bf16 v[88:91], v[194:197], v[218:221], v[88:91]
	v_mfma_f32_16x16x32_bf16 v[80:83], v[202:205], v[218:221], v[80:83]
	v_mfma_f32_16x16x32_bf16 v[76:79], v[194:197], v[226:229], v[76:79]
	v_mfma_f32_16x16x32_bf16 v[72:75], v[202:205], v[226:229], v[72:75]
	v_mfma_f32_16x16x32_bf16 v[68:71], v[194:197], v[234:237], v[68:71]
	v_mfma_f32_16x16x32_bf16 v[64:67], v[202:205], v[234:237], v[64:67]
	v_mfma_f32_16x16x32_bf16 v[104:107], v[198:201], v[214:217], v[104:107]
	v_mfma_f32_16x16x32_bf16 v[96:99], v[206:209], v[214:217], v[96:99]
	v_mfma_f32_16x16x32_bf16 v[88:91], v[198:201], v[222:225], v[88:91]
	v_mfma_f32_16x16x32_bf16 v[80:83], v[206:209], v[222:225], v[80:83]
	v_mfma_f32_16x16x32_bf16 v[76:79], v[198:201], v[230:233], v[76:79]
	v_mfma_f32_16x16x32_bf16 v[72:75], v[206:209], v[230:233], v[72:75]
	v_mfma_f32_16x16x32_bf16 v[68:71], v[198:201], v[238:241], v[68:71]
	v_mfma_f32_16x16x32_bf16 v[64:67], v[206:209], v[238:241], v[64:67]
	s_setprio 0
	s_barrier
	s_add_i32 s74, s75, s81
	v_lshl_add_u64 v[242:243], s[48:49], 0, v[130:131]
	s_mov_b32 m0, s74
	ds_read_b128 v[210:213], v180 offset:16384
	ds_read_b128 v[214:217], v180 offset:17408
	ds_read_b128 v[218:221], v180 offset:18432
	ds_read_b128 v[222:225], v180 offset:19456
	ds_read_b128 v[226:229], v180 offset:20480
	ds_read_b128 v[230:233], v180 offset:21504
	ds_read_b128 v[234:237], v180 offset:22528
	ds_read_b128 v[238:241], v180 offset:23552
	global_load_lds_dwordx4 v[242:243], off
	s_add_i32 m0, s74, 0x2000
	s_add_u32 s74, s48, 0x40000
	v_lshl_add_u64 v[244:245], s[48:49], 0, v[132:133]
	s_addc_u32 s75, s49, 0
	s_add_i32 s73, s73, s81
	global_load_lds_dwordx4 v[244:245], off
	v_lshl_add_u64 v[246:247], s[74:75], 0, v[130:131]
	s_mov_b32 m0, s73
	v_lshl_add_u64 v[248:249], s[50:51], 0, v[132:133]
	global_load_lds_dwordx4 v[246:247], off
	s_add_i32 m0, s73, 0x2000
	v_lshl_add_u64 v[246:247], s[74:75], 0, v[132:133]
	global_load_lds_dwordx4 v[246:247], off
	s_mov_b32 m0, s52
	v_lshl_add_u64 v[246:247], s[50:51], 0, v[130:131]
	global_load_lds_dwordx4 v[246:247], off
	s_mov_b32 m0, s57
	s_nop 0
	global_load_lds_dwordx4 v[248:249], off
	s_waitcnt vmcnt(8) lgkmcnt(0)
	s_barrier
; #define PG8_STAGE(bufoff, gbase, voff) do { _Pragma("unroll") for (int _i = 0; _i < 2; ++_i) \
;         __builtin_amdgcn_global_load_lds((const unsigned*)((const char*)(gbase) + (voff)[_i]), (LAS unsigned*)(lds + (bufoff) + ldsw + _i * 8192), 16, 0, 0); } while (0)
; #define PG8_LDA(dst, b, h) do { _Pragma("unroll") for (int m = 0; m < 4; ++m) _Pragma("unroll") for (int k = 0; k < 2; ++k) dst[m][k] = *(const LAS bf16x8*)(lds + PG8_SA(b, h) + aoff + m * 2048 + k * 1024); } while (0)
; #define PG8_LDB(dst, b, h) do { _Pragma("unroll") for (int n = 0; n < 2; ++n) _Pragma("unroll") for (int k = 0; k < 2; ++k) dst[n][k] = *(const LAS bf16x8*)(lds + PG8_SB(b, h) + boff + n * 2048 + k * 1024); } while (0)
; #define PG8_MMA(ai, bj, At, Bt) do { __builtin_amdgcn_s_setprio(1); _Pragma("unroll") for (int m = 0; m < 4; ++m) _Pragma("unroll") for (int n = 0; n < 2; ++n) _Pragma("unroll") for (int k = 0; k < 2; ++k) \
;         acc[ai][bj][m][n] = __builtin_amdgcn_mfma_f32_16x16x32_bf16(Bt[n][k], At[m][k], acc[ai][bj][m][n], 0, 0, 0); __builtin_amdgcn_s_setprio(0); } while (0)
; #define PG8_WAIT_V(n) asm volatile("s_waitcnt vmcnt(" #n ")" ::: "memory")
; #define PG8_WAIT_L(n) asm volatile("s_waitcnt lgkmcnt(" #n ")" ::: "memory")
; #define PG8_BAR __builtin_amdgcn_s_barrier()
; #define PG8_SCHED __builtin_amdgcn_sched_barrier(0)
; template <class Epi, class Sched>
; __device__ __forceinline__ void gemm_phase(LAS unsigned char* lds, const Gemm g, const Sched& S, const Epi& E, const int wave_s) {
;     ...
;             PG8_WAIT_V(8); PG8_WAIT_L(0); PG8_BAR; PG8_MMA(1, 0, At, B0); PG8_MMA(1, 1, At, B1); PG8_BAR; PG8_SCHED;
;             PG8_LDB(B0, 1, 0); PG8_LDB(B1, 1, 1); PG8_SCHED; PG8_LDA(At, 1, 0); PG8_STAGE(PG8_SA(0, 1), a2 + hstepA, voffA);
;             PG8_WAIT_V(8); PG8_WAIT_L(0); PG8_BAR; PG8_MMA(0, 0, At, B0); PG8_MMA(0, 1, At, B1); PG8_BAR; PG8_SCHED;
	s_setprio 1
	v_mfma_f32_16x16x32_bf16 v[60:63], v[170:173], v[210:213], v[60:63]
	v_mfma_f32_16x16x32_bf16 v[56:59], v[186:189], v[210:213], v[56:59]
	v_mfma_f32_16x16x32_bf16 v[52:55], v[170:173], v[218:221], v[52:55]
	v_mfma_f32_16x16x32_bf16 v[48:51], v[186:189], v[218:221], v[48:51]
	v_mfma_f32_16x16x32_bf16 v[44:47], v[170:173], v[226:229], v[44:47]
	v_mfma_f32_16x16x32_bf16 v[36:39], v[186:189], v[226:229], v[36:39]
	v_mfma_f32_16x16x32_bf16 v[28:31], v[170:173], v[234:237], v[28:31]
	v_mfma_f32_16x16x32_bf16 v[20:23], v[186:189], v[234:237], v[20:23]
	v_mfma_f32_16x16x32_bf16 v[60:63], v[182:185], v[214:217], v[60:63]
	v_mfma_f32_16x16x32_bf16 v[56:59], v[190:193], v[214:217], v[56:59]
	v_mfma_f32_16x16x32_bf16 v[52:55], v[182:185], v[222:225], v[52:55]
	v_mfma_f32_16x16x32_bf16 v[48:51], v[190:193], v[222:225], v[48:51]
	v_mfma_f32_16x16x32_bf16 v[44:47], v[182:185], v[230:233], v[44:47]
	v_mfma_f32_16x16x32_bf16 v[36:39], v[190:193], v[230:233], v[36:39]
	v_mfma_f32_16x16x32_bf16 v[28:31], v[182:185], v[238:241], v[28:31]
	v_mfma_f32_16x16x32_bf16 v[20:23], v[190:193], v[238:241], v[20:23]
	s_setprio 0
	s_setprio 1
	v_mfma_f32_16x16x32_bf16 v[40:43], v[194:197], v[210:213], v[40:43]
	v_mfma_f32_16x16x32_bf16 v[32:35], v[202:205], v[210:213], v[32:35]
	v_mfma_f32_16x16x32_bf16 v[24:27], v[194:197], v[218:221], v[24:27]
	v_mfma_f32_16x16x32_bf16 v[16:19], v[202:205], v[218:221], v[16:19]
	v_mfma_f32_16x16x32_bf16 v[12:15], v[194:197], v[226:229], v[12:15]
	v_mfma_f32_16x16x32_bf16 v[8:11], v[202:205], v[226:229], v[8:11]
	v_mfma_f32_16x16x32_bf16 v[4:7], v[194:197], v[234:237], v[4:7]
	v_mfma_f32_16x16x32_bf16 v[0:3], v[202:205], v[234:237], v[0:3]
	v_mfma_f32_16x16x32_bf16 v[40:43], v[198:201], v[214:217], v[40:43]
	v_mfma_f32_16x16x32_bf16 v[32:35], v[206:209], v[214:217], v[32:35]
	v_mfma_f32_16x16x32_bf16 v[24:27], v[198:201], v[222:225], v[24:27]
	v_mfma_f32_16x16x32_bf16 v[16:19], v[206:209], v[222:225], v[16:19]
	v_mfma_f32_16x16x32_bf16 v[12:15], v[198:201], v[230:233], v[12:15]
	v_mfma_f32_16x16x32_bf16 v[8:11], v[206:209], v[230:233], v[8:11]
	v_mfma_f32_16x16x32_bf16 v[4:7], v[198:201], v[238:241], v[4:7]
	v_mfma_f32_16x16x32_bf16 v[0:3], v[206:209], v[238:241], v[0:3]
	s_setprio 0
	s_barrier
	s_add_i32 s73, 0, 0x18000
	v_add_u32_e32 v128, s73, v178
	s_add_i32 s74, 0, 0x1c000
	ds_read_b128 v[170:173], v128
	ds_read_b128 v[182:185], v128 offset:1024
	ds_read_b128 v[186:189], v128 offset:2048
	ds_read_b128 v[190:193], v128 offset:3072
	v_add_u32_e32 v128, s74, v178
	ds_read_b128 v[194:197], v128
	ds_read_b128 v[198:201], v128 offset:1024
	ds_read_b128 v[202:205], v128 offset:2048
	ds_read_b128 v[206:209], v128 offset:3072
	s_add_u32 s50, s50, 0x40000
	s_addc_u32 s51, s51, 0
	s_mov_b32 m0, s58
	v_lshl_add_u64 v[250:251], s[50:51], 0, v[130:131]
	ds_read_b128 v[210:213], v180 offset:32768
	ds_read_b128 v[214:217], v180 offset:33792
	ds_read_b128 v[218:221], v180 offset:34816
	ds_read_b128 v[222:225], v180 offset:35840
	ds_read_b128 v[226:229], v180 offset:36864
	ds_read_b128 v[230:233], v180 offset:37888
	ds_read_b128 v[234:237], v180 offset:38912
	ds_read_b128 v[238:241], v180 offset:39936
	global_load_lds_dwordx4 v[250:251], off
	s_mov_b32 m0, s59
	v_lshl_add_u64 v[250:251], s[50:51], 0, v[132:133]
	global_load_lds_dwordx4 v[250:251], off
	s_waitcnt vmcnt(8) lgkmcnt(0)
	s_barrier
	s_setprio 1
	v_mfma_f32_16x16x32_bf16 v[124:127], v[170:173], v[210:213], v[124:127]
	v_mfma_f32_16x16x32_bf16 v[120:123], v[186:189], v[210:213], v[120:123]
	v_mfma_f32_16x16x32_bf16 v[116:119], v[170:173], v[218:221], v[116:119]
	v_mfma_f32_16x16x32_bf16 v[112:115], v[186:189], v[218:221], v[112:115]
	v_mfma_f32_16x16x32_bf16 v[108:111], v[170:173], v[226:229], v[108:111]
	v_mfma_f32_16x16x32_bf16 v[100:103], v[186:189], v[226:229], v[100:103]
	v_mfma_f32_16x16x32_bf16 v[92:95], v[170:173], v[234:237], v[92:95]
	v_mfma_f32_16x16x32_bf16 v[84:87], v[186:189], v[234:237], v[84:87]
	v_mfma_f32_16x16x32_bf16 v[124:127], v[182:185], v[214:217], v[124:127]
	v_mfma_f32_16x16x32_bf16 v[120:123], v[190:193], v[214:217], v[120:123]
	v_mfma_f32_16x16x32_bf16 v[116:119], v[182:185], v[222:225], v[116:119]
	v_mfma_f32_16x16x32_bf16 v[112:115], v[190:193], v[222:225], v[112:115]
	v_mfma_f32_16x16x32_bf16 v[108:111], v[182:185], v[230:233], v[108:111]
	v_mfma_f32_16x16x32_bf16 v[100:103], v[190:193], v[230:233], v[100:103]
	v_mfma_f32_16x16x32_bf16 v[92:95], v[182:185], v[238:241], v[92:95]
	v_mfma_f32_16x16x32_bf16 v[84:87], v[190:193], v[238:241], v[84:87]
	s_setprio 0
	s_setprio 1
	v_mfma_f32_16x16x32_bf16 v[104:107], v[194:197], v[210:213], v[104:107]
	v_mfma_f32_16x16x32_bf16 v[96:99], v[202:205], v[210:213], v[96:99]
	v_mfma_f32_16x16x32_bf16 v[88:91], v[194:197], v[218:221], v[88:91]
	v_mfma_f32_16x16x32_bf16 v[80:83], v[202:205], v[218:221], v[80:83]
	v_mfma_f32_16x16x32_bf16 v[76:79], v[194:197], v[226:229], v[76:79]
	v_mfma_f32_16x16x32_bf16 v[72:75], v[202:205], v[226:229], v[72:75]
	v_mfma_f32_16x16x32_bf16 v[68:71], v[194:197], v[234:237], v[68:71]
	v_mfma_f32_16x16x32_bf16 v[64:67], v[202:205], v[234:237], v[64:67]
	v_mfma_f32_16x16x32_bf16 v[104:107], v[198:201], v[214:217], v[104:107]
	v_mfma_f32_16x16x32_bf16 v[96:99], v[206:209], v[214:217], v[96:99]
	v_mfma_f32_16x16x32_bf16 v[88:91], v[198:201], v[222:225], v[88:91]
	v_mfma_f32_16x16x32_bf16 v[80:83], v[206:209], v[222:225], v[80:83]
	v_mfma_f32_16x16x32_bf16 v[76:79], v[198:201], v[230:233], v[76:79]
	v_mfma_f32_16x16x32_bf16 v[72:75], v[206:209], v[230:233], v[72:75]
	v_mfma_f32_16x16x32_bf16 v[68:71], v[198:201], v[238:241], v[68:71]
	v_mfma_f32_16x16x32_bf16 v[64:67], v[206:209], v[238:241], v[64:67]
	s_setprio 0
	s_barrier
; #define PG8_STAGE(bufoff, gbase, voff) do { _Pragma("unroll") for (int _i = 0; _i < 2; ++_i) \
;         __builtin_amdgcn_global_load_lds((const unsigned*)((const char*)(gbase) + (voff)[_i]), (LAS unsigned*)(lds + (bufoff) + ldsw + _i * 8192), 16, 0, 0); } while (0)
; #define PG8_LDA(dst, b, h) do { _Pragma("unroll") for (int m = 0; m < 4; ++m) _Pragma("unroll") for (int k = 0; k < 2; ++k) dst[m][k] = *(const LAS bf16x8*)(lds + PG8_SA(b, h) + aoff + m * 2048 + k * 1024); } while (0)
; #define PG8_MMA(ai, bj, At, Bt) do { __builtin_amdgcn_s_setprio(1); _Pragma("unroll") for (int m = 0; m < 4; ++m) _Pragma("unroll") for (int n = 0; n < 2; ++n) _Pragma("unroll") for (int k = 0; k < 2; ++k) \
;         acc[ai][bj][m][n] = __builtin_amdgcn_mfma_f32_16x16x32_bf16(Bt[n][k], At[m][k], acc[ai][bj][m][n], 0, 0, 0); __builtin_amdgcn_s_setprio(0); } while (0)
; #define PG8_WAIT_V(n) asm volatile("s_waitcnt vmcnt(" #n ")" ::: "memory")
; #define PG8_WAIT_L(n) asm volatile("s_waitcnt lgkmcnt(" #n ")" ::: "memory")
; #define PG8_BAR __builtin_amdgcn_s_barrier()
; #define PG8_SCHED __builtin_amdgcn_sched_barrier(0)
; template <class Epi, class Sched>
; __device__ __forceinline__ void gemm_phase(LAS unsigned char* lds, const Gemm g, const Sched& S, const Epi& E, const int wave_s) {
;     ...
;             PG8_LDA(At, 1, 1); PG8_STAGE(PG8_SB(1, 0), b3, voffB); PG8_STAGE(PG8_SB(1, 1), b3 + hstepB, voffB); PG8_STAGE(PG8_SA(1, 0), a3, voffA);
;             PG8_WAIT_V(8); PG8_WAIT_L(0); PG8_BAR; PG8_MMA(1, 0, At, B0); PG8_MMA(1, 1, At, B1); PG8_BAR; PG8_SCHED;
;         }
	s_add_i32 s50, s73, s81
	v_lshl_add_u64 v[242:243], v[242:243], 0, s[22:23]
	s_mov_b32 m0, s50
	ds_read_b128 v[210:213], v180 offset:49152
	ds_read_b128 v[214:217], v180 offset:50176
	ds_read_b128 v[218:221], v180 offset:51200
	ds_read_b128 v[222:225], v180 offset:52224
	ds_read_b128 v[226:229], v180 offset:53248
	ds_read_b128 v[230:233], v180 offset:54272
	ds_read_b128 v[234:237], v180 offset:55296
	ds_read_b128 v[238:241], v180 offset:56320
	global_load_lds_dwordx4 v[242:243], off
	s_add_i32 m0, s50, 0x2000
	s_add_u32 s48, s48, 0x40080
	v_lshl_add_u64 v[242:243], v[244:245], 0, s[22:23]
	s_addc_u32 s49, s49, 0
	s_add_i32 s50, s74, s81
	global_load_lds_dwordx4 v[242:243], off
	s_mov_b32 m0, s50
	v_lshl_add_u64 v[242:243], s[48:49], 0, v[130:131]
	global_load_lds_dwordx4 v[242:243], off
	s_add_i32 m0, s50, 0x2000
	v_lshl_add_u64 v[242:243], s[48:49], 0, v[132:133]
	global_load_lds_dwordx4 v[242:243], off
	s_mov_b32 m0, s20
	v_lshl_add_u64 v[242:243], v[246:247], 0, s[22:23]
	global_load_lds_dwordx4 v[242:243], off
	s_mov_b32 m0, s63
	v_lshl_add_u64 v[242:243], v[248:249], 0, s[22:23]
	global_load_lds_dwordx4 v[242:243], off
	s_waitcnt vmcnt(8) lgkmcnt(0)
	s_barrier
	s_setprio 1
	v_mfma_f32_16x16x32_bf16 v[60:63], v[170:173], v[210:213], v[60:63]
	v_mfma_f32_16x16x32_bf16 v[56:59], v[186:189], v[210:213], v[56:59]
	v_mfma_f32_16x16x32_bf16 v[52:55], v[170:173], v[218:221], v[52:55]
	v_mfma_f32_16x16x32_bf16 v[48:51], v[186:189], v[218:221], v[48:51]
	v_mfma_f32_16x16x32_bf16 v[44:47], v[170:173], v[226:229], v[44:47]
	v_mfma_f32_16x16x32_bf16 v[36:39], v[186:189], v[226:229], v[36:39]
	v_mfma_f32_16x16x32_bf16 v[28:31], v[170:173], v[234:237], v[28:31]
	v_mfma_f32_16x16x32_bf16 v[20:23], v[186:189], v[234:237], v[20:23]
	v_mfma_f32_16x16x32_bf16 v[60:63], v[182:185], v[214:217], v[60:63]
	v_mfma_f32_16x16x32_bf16 v[56:59], v[190:193], v[214:217], v[56:59]
	v_mfma_f32_16x16x32_bf16 v[52:55], v[182:185], v[222:225], v[52:55]
	v_mfma_f32_16x16x32_bf16 v[48:51], v[190:193], v[222:225], v[48:51]
	v_mfma_f32_16x16x32_bf16 v[44:47], v[182:185], v[230:233], v[44:47]
	v_mfma_f32_16x16x32_bf16 v[36:39], v[190:193], v[230:233], v[36:39]
	v_mfma_f32_16x16x32_bf16 v[28:31], v[182:185], v[238:241], v[28:31]
	v_mfma_f32_16x16x32_bf16 v[20:23], v[190:193], v[238:241], v[20:23]
	s_setprio 0
	s_setprio 1
	v_mfma_f32_16x16x32_bf16 v[40:43], v[194:197], v[210:213], v[40:43]
	v_mfma_f32_16x16x32_bf16 v[32:35], v[202:205], v[210:213], v[32:35]
	v_mfma_f32_16x16x32_bf16 v[24:27], v[194:197], v[218:221], v[24:27]
	v_mfma_f32_16x16x32_bf16 v[16:19], v[202:205], v[218:221], v[16:19]
	v_mfma_f32_16x16x32_bf16 v[12:15], v[194:197], v[226:229], v[12:15]
	v_mfma_f32_16x16x32_bf16 v[8:11], v[202:205], v[226:229], v[8:11]
	v_mfma_f32_16x16x32_bf16 v[4:7], v[194:197], v[234:237], v[4:7]
	v_mfma_f32_16x16x32_bf16 v[0:3], v[202:205], v[234:237], v[0:3]
	v_mfma_f32_16x16x32_bf16 v[40:43], v[198:201], v[214:217], v[40:43]
	v_mfma_f32_16x16x32_bf16 v[32:35], v[206:209], v[214:217], v[32:35]
	v_mfma_f32_16x16x32_bf16 v[24:27], v[198:201], v[222:225], v[24:27]
	v_mfma_f32_16x16x32_bf16 v[16:19], v[206:209], v[222:225], v[16:19]
	v_mfma_f32_16x16x32_bf16 v[12:15], v[198:201], v[230:233], v[12:15]
	v_mfma_f32_16x16x32_bf16 v[8:11], v[206:209], v[230:233], v[8:11]
	v_mfma_f32_16x16x32_bf16 v[4:7], v[198:201], v[238:241], v[4:7]
	v_mfma_f32_16x16x32_bf16 v[0:3], v[206:209], v[238:241], v[0:3]
	s_setprio 0
	s_barrier
	s_add_i32 s72, s72, 2
	s_add_u32 s46, s46, 0x100
	s_addc_u32 s47, s47, 0
	s_cmp_gt_u32 s72, 13
	s_cbranch_scc0 .LBB0_1024
	s_and_b64 vcc, exec, s[12:13]
	s_cbranch_vccz .LBB0_1027
	s_barrier
